# P7 epilogue: staging load of conv taps issued before the K loop (no exposed wait at the epilogue barrier); sample-only conv-state waits made conditional; dead spill reloads removed
# baseline (speedup 1.0000x reference)
; #define LAS __attribute__((address_space(3)))
; #define PG8_BAR __builtin_amdgcn_s_barrier()
; template <class Epi, class Sched>
; DI void gemm_phase(LAS unsigned char* lds, const int K, const Sched& S, const Epi& E, const int wid) {
;     ...
; #pragma unroll
;         for (int a = 0; a < 2; ++a)
; #pragma unroll
;             for (int b = 0; b < 2; ++b)
; #pragma unroll
;                 for (int m = 0; m < 4; ++m)
; #pragma unroll
;                     for (int n = 0; n < 2; ++n) acc[a][b][m][n] = (f32x4){0.f, 0.f, 0.f, 0.f};
;         cur = nxt; cA = nA; cB = nB; ++ui;
;         if (wr == 1) PG8_BAR;
;     DI void operator()(const Acc& acc, const Unit& u, int wr, int wc, int fr, int fq) const {
;     ...
;             if (t < 256) { const int q = t >> 5, f4 = (t & 31) * 4, gv = q >> 2, tap = q & 3;
;                 *(LAS f32x4*)(cwl + q * 128 + f4) = *(const f32x4*)((tap < 3 ? w_conv + (size_t)tap * FF2 : b_conv) + gv * FF + u.pn * 128 + f4); }
;             else if (t < 320) *(LAS f32x4*)(ssl + (t - 256) * 4) = *(const f32x4*)(ss1 + (size_t)u.pm * 256 + (t - 256) * 4);
.LBB0_812:
	s_ashr_i32 s35, s34, 31
	s_lshl_b64 s[4:5], s[34:35], 20
	v_readlane_b32 s2, v249, 9
	v_readlane_b32 s3, v249, 10
	s_add_u32 s36, s2, s4
	s_addc_u32 s37, s3, s5
	s_and_b64 s[4:5], exec, s[42:43]
	s_cselect_b32 s35, s51, s37
	s_cselect_b32 s45, s50, s36
	s_ashr_i32 s31, s30, 31
	s_lshl_b64 s[4:5], s[30:31], 20
	v_readlane_b32 s2, v250, 41
	v_readlane_b32 s3, v250, 42
	s_add_u32 s38, s2, s4
	s_addc_u32 s39, s3, s5
	s_and_b64 s[4:5], exec, s[42:43]
	s_cselect_b32 s31, s49, s39
	s_cselect_b32 s47, s48, s38
	v_mov_b32_e32 v8, 0
	s_cmpk_lt_i32 s34, 0x80
	v_readlane_b32 s2, v249, 1
	s_mov_b32 s54, 0
	s_cselect_b64 s[52:53], -1, 0
	v_mov_b32_e32 v9, v8
	v_mov_b32_e32 v10, v8
	v_mov_b32_e32 v11, v8
	v_mov_b32_e32 v72, v8
	v_mov_b32_e32 v73, v8
	v_mov_b32_e32 v74, v8
	v_mov_b32_e32 v75, v8
	v_mov_b32_e32 v0, v8
	v_mov_b32_e32 v1, v8
	v_mov_b32_e32 v2, v8
	v_mov_b32_e32 v3, v8
	v_mov_b32_e32 v64, v8
	v_mov_b32_e32 v65, v8
	v_mov_b32_e32 v66, v8
	v_mov_b32_e32 v67, v8
	v_mov_b32_e32 v4, v8
	v_mov_b32_e32 v5, v8
	v_mov_b32_e32 v6, v8
	v_mov_b32_e32 v7, v8
	v_mov_b32_e32 v68, v8
	v_mov_b32_e32 v69, v8
	v_mov_b32_e32 v70, v8
	v_mov_b32_e32 v71, v8
	v_mov_b32_e32 v12, v8
	v_mov_b32_e32 v13, v8
	v_mov_b32_e32 v14, v8
	v_mov_b32_e32 v15, v8
	v_mov_b32_e32 v76, v8
	v_mov_b32_e32 v77, v8
	v_mov_b32_e32 v78, v8
	v_mov_b32_e32 v79, v8
	v_mov_b32_e32 v24, v8
	v_mov_b32_e32 v25, v8
	v_mov_b32_e32 v26, v8
	v_mov_b32_e32 v27, v8
	v_mov_b32_e32 v88, v8
	v_mov_b32_e32 v89, v8
	v_mov_b32_e32 v90, v8
	v_mov_b32_e32 v91, v8
	v_mov_b32_e32 v16, v8
	v_mov_b32_e32 v17, v8
	v_mov_b32_e32 v18, v8
	v_mov_b32_e32 v19, v8
	v_mov_b32_e32 v80, v8
	v_mov_b32_e32 v81, v8
	v_mov_b32_e32 v82, v8
	v_mov_b32_e32 v83, v8
	v_mov_b32_e32 v20, v8
	v_mov_b32_e32 v21, v8
	v_mov_b32_e32 v22, v8
	v_mov_b32_e32 v23, v8
	v_mov_b32_e32 v84, v8
	v_mov_b32_e32 v85, v8
	v_mov_b32_e32 v86, v8
	v_mov_b32_e32 v87, v8
	v_mov_b32_e32 v28, v8
	v_mov_b32_e32 v29, v8
	v_mov_b32_e32 v30, v8
	v_mov_b32_e32 v31, v8
	v_mov_b32_e32 v92, v8
	v_mov_b32_e32 v93, v8
	v_mov_b32_e32 v94, v8
	v_mov_b32_e32 v95, v8
	v_mov_b32_e32 v40, v8
	v_mov_b32_e32 v41, v8
	v_mov_b32_e32 v42, v8
	v_mov_b32_e32 v43, v8
	v_mov_b32_e32 v136, v8
	v_mov_b32_e32 v137, v8
	v_mov_b32_e32 v138, v8
	v_mov_b32_e32 v139, v8
	v_mov_b32_e32 v32, v8
	v_mov_b32_e32 v33, v8
	v_mov_b32_e32 v34, v8
	v_mov_b32_e32 v35, v8
	v_mov_b32_e32 v128, v8
	v_mov_b32_e32 v129, v8
	v_mov_b32_e32 v130, v8
	v_mov_b32_e32 v131, v8
	v_mov_b32_e32 v36, v8
	v_mov_b32_e32 v37, v8
	v_mov_b32_e32 v38, v8
	v_mov_b32_e32 v39, v8
	v_mov_b32_e32 v132, v8
	v_mov_b32_e32 v133, v8
	v_mov_b32_e32 v134, v8
	v_mov_b32_e32 v135, v8
	v_mov_b32_e32 v44, v8
	v_mov_b32_e32 v45, v8
	v_mov_b32_e32 v46, v8
	v_mov_b32_e32 v47, v8
	v_mov_b32_e32 v140, v8
	v_mov_b32_e32 v141, v8
	v_mov_b32_e32 v142, v8
	v_mov_b32_e32 v143, v8
	v_mov_b32_e32 v56, v8
	v_mov_b32_e32 v57, v8
	v_mov_b32_e32 v58, v8
	v_mov_b32_e32 v59, v8
	v_mov_b32_e32 v152, v8
	v_mov_b32_e32 v153, v8
	v_mov_b32_e32 v154, v8
	v_mov_b32_e32 v155, v8
	v_mov_b32_e32 v48, v8
	v_mov_b32_e32 v49, v8
	v_mov_b32_e32 v50, v8
	v_mov_b32_e32 v51, v8
	v_mov_b32_e32 v144, v8
	v_mov_b32_e32 v145, v8
	v_mov_b32_e32 v146, v8
	v_mov_b32_e32 v147, v8
	v_mov_b32_e32 v52, v8
	v_mov_b32_e32 v53, v8
	v_mov_b32_e32 v54, v8
	v_mov_b32_e32 v55, v8
	v_mov_b32_e32 v148, v8
	v_mov_b32_e32 v149, v8
	v_mov_b32_e32 v150, v8
	v_mov_b32_e32 v151, v8
	v_mov_b32_e32 v60, v8
	v_mov_b32_e32 v61, v8
	v_mov_b32_e32 v62, v8
	v_mov_b32_e32 v63, v8
	v_mov_b32_e32 v156, v8
	v_mov_b32_e32 v157, v8
	v_mov_b32_e32 v158, v8
	v_mov_b32_e32 v159, v8
	v_readlane_b32 s3, v249, 2
	s_cmp_gt_u32 s76, 0x100
	s_cbranch_scc1 .Lup_stage_done
	v_lshlrev_b32_e32 v236, 4, v197
	v_mov_b32_e32 v241, 0
	s_nop 0
	v_add3_u32 v236, s76, v196, v236
	s_cmp_eq_u32 s76, 0x100
	s_cbranch_scc1 .Lup_stage_ss
	v_readlane_b32 s98, v250, 55
	v_readlane_b32 s99, v250, 56
	v_readlane_b32 s100, v250, 57
	v_readlane_b32 s101, v250, 58
	v_lshrrev_b32_e32 v237, 5, v236
	v_and_b32_e32 v237, 3, v237
	v_lshrrev_b32_e32 v239, 7, v236
	v_mul_u32_u24_e32 v240, 0xb000, v237
	v_mul_u32_u24_e32 v239, 0x5800, v239
	v_lshlrev_b32_e32 v242, 4, v236
	v_and_b32_e32 v242, 0x1f0, v242
	v_lshl_add_u32 v242, s44, 9, v242
	v_cmp_eq_u32_e32 vcc, 3, v237
	v_mov_b32_e32 v238, s98
	v_mov_b32_e32 v243, s100
	s_nop 1
	v_cndmask_b32_e64 v240, v240, 0, vcc
	v_cndmask_b32_e32 v238, v238, v243, vcc
	v_mov_b32_e32 v243, s101
	v_mov_b32_e32 v237, s99
	v_add3_u32 v240, v240, v239, v242
	v_cndmask_b32_e32 v239, v237, v243, vcc
	s_nop 1
	v_lshl_add_u64 v[238:239], v[238:239], 0, v[240:241]
	s_nop 1
	global_load_dwordx4 v[244:247], v[238:239], off
	s_branch .Lup_stage_done
.Lup_stage_ss:
	v_readlane_b32 s98, v249, 30
	v_readlane_b32 s99, v249, 31
	s_lshl_b32 s100, s0, 10
	v_lshlrev_b32_e32 v240, 4, v236
	s_nop 1
	v_add_u32_e32 v240, s100, v240
	s_nop 1
	v_lshl_add_u64 v[238:239], s[98:99], 0, v[240:241]
	s_nop 1
	global_load_dwordx4 v[244:247], v[238:239], off offset:-4096
.Lup_stage_done:
	s_branch .LBB0_815
.LBB0_813:
	s_waitcnt lgkmcnt(0)
	buffer_inv sc1

; #define LAS __attribute__((address_space(3)))
;     DI void operator()(const Acc& acc, const Unit& u, int wr, int wc, int fr, int fq) const {
;     ...
;             if (t < 256) { const int q = t >> 5, f4 = (t & 31) * 4, gv = q >> 2, tap = q & 3;
;                 *(LAS f32x4*)(cwl + q * 128 + f4) = *(const f32x4*)((tap < 3 ? w_conv + (size_t)tap * FF2 : b_conv) + gv * FF + u.pn * 128 + f4); }
;             else if (t < 320) *(LAS f32x4*)(ssl + (t - 256) * 4) = *(const f32x4*)(ss1 + (size_t)u.pm * 256 + (t - 256) * 4);
;             asm volatile("s_waitcnt lgkmcnt(0)" ::: "memory");
;             __builtin_amdgcn_s_barrier();
.LBB0_820:
	v_mov_b32_e32 v203, v196
	v_mov_b32_e32 v96, v197
	s_movk_i32 s4, 0xff
	v_lshlrev_b32_e32 v97, 4, v96
	v_add3_u32 v97, s76, v203, v97
	v_cmp_lt_i32_e32 vcc, s4, v97
	s_and_saveexec_b64 s[4:5], vcc
	s_xor_b64 s[4:5], exec, s[4:5]
	s_cbranch_execz .LBB0_824
	s_movk_i32 s6, 0x140
	v_cmp_gt_u32_e32 vcc, s6, v97
	s_and_saveexec_b64 s[6:7], vcc
	s_cbranch_execz .LBB0_823
	s_ashr_i32 s1, s0, 31
	s_lshl_b64 s[42:43], s[0:1], 10
	v_readlane_b32 s48, v249, 30
	v_readlane_b32 s49, v249, 31
	s_add_u32 s42, s48, s42
	v_lshlrev_b32_e32 v168, 2, v97
	s_addc_u32 s43, s49, s43
	v_lshl_add_u64 v[98:99], v[168:169], 2, s[42:43]
	v_lshl_add_u32 v97, v97, 4, 0
	v_add_u32_e32 v97, 0x20400, v97
	ds_write_b128 v97, v[244:247]

; #define LAS __attribute__((address_space(3)))
;     DI void operator()(const Acc& acc, const Unit& u, int wr, int wc, int fr, int fq) const {
;     ...
;             if (t < 256) { const int q = t >> 5, f4 = (t & 31) * 4, gv = q >> 2, tap = q & 3;
;                 *(LAS f32x4*)(cwl + q * 128 + f4) = *(const f32x4*)((tap < 3 ? w_conv + (size_t)tap * FF2 : b_conv) + gv * FF + u.pn * 128 + f4); }
.LBB0_824:
	s_or_saveexec_b64 s[4:5], s[4:5]
	s_lshl_b32 s6, s44, 7
	s_xor_b64 exec, exec, s[4:5]
	s_cbranch_execz .LBB0_826
	v_ashrrev_i32_e32 v102, 5, v97
	v_and_b32_e32 v101, 3, v102
	v_mul_u32_u24_e32 v98, 0x2c00, v101
	v_readlane_b32 s54, v250, 55
	v_readlane_b32 s55, v250, 56
	v_readlane_b32 s56, v250, 57
	v_readlane_b32 s57, v250, 58
	v_lshrrev_b32_e32 v100, 7, v97
	v_lshlrev_b32_e32 v168, 2, v98
	s_mov_b64 s[42:43], s[54:55]
	s_mov_b64 s[44:45], s[56:57]
	s_movk_i32 s7, 0x1600
	v_lshl_add_u64 v[98:99], s[42:43], 0, v[168:169]
	v_mov_b32_e32 v103, s45
	v_cmp_eq_u32_e32 vcc, 3, v101
	v_mov_b32_e32 v101, s44
	v_mul_lo_u32 v100, v100, s7
	v_cndmask_b32_e32 v99, v99, v103, vcc
	v_cndmask_b32_e32 v98, v98, v101, vcc
	v_ashrrev_i32_e32 v101, 31, v100
	v_lshl_add_u64 v[98:99], v[100:101], 2, v[98:99]
	s_ashr_i32 s7, s6, 31
	v_lshlrev_b32_e32 v97, 4, v97
	v_lshl_add_u64 v[98:99], s[6:7], 2, v[98:99]
	v_and_b32_e32 v168, 0x1f0, v97
	v_lshl_add_u64 v[98:99], v[98:99], 0, v[168:169]
	v_lshlrev_b32_e32 v97, 9, v102
	s_add_i32 s7, 0, 0x20400
	v_add3_u32 v97, s7, v97, v168
	ds_write_b128 v97, v[244:247]

;     template <int GV>
;     DI void conv_cols(const Acc& acc, const Unit& u, int ai, int n, int G, int f, int fr, const float (&rs)[4], bool samp, int sb, const f32x4 (&cw)[4], f32x4 (&cg)[4], bf16_t* actp) const {
;     ...
;         for (int m = 0; m < 4; ++m) X[m] = acc[ai][GV][m][n] * rs[m];
;         f32x4 Hh = (f32x4){0.f, 0.f, 0.f, 0.f};
;         if (samp) { if (fr >= 14) Hh = *(const f32x4*)(sconv + ((size_t)sb * 2 + (fr - 14)) * FF2 + GV * FF + f); }
.LBB0_830:
	s_lshl_b32 s64, s0, 2
	s_add_i32 s20, s64, 0xfffffe00
	v_readlane_b32 s1, v249, 24
	s_add_i32 s10, s20, s1
	v_mov_b32_e32 v156, 0
	s_andn2_b64 vcc, exec, s[6:7]
	v_mov_b32_e32 v157, 0
	v_mov_b32_e32 v158, 0
	v_mov_b32_e32 v159, 0
	s_cbranch_vccnz .LBB0_834
	v_mov_b32_e32 v159, 0
	v_mov_b32_e32 v158, 0
	v_mov_b32_e32 v157, 0
	v_mov_b32_e32 v156, 0
	s_and_saveexec_b64 s[6:7], s[42:43]
	s_cbranch_execz .LBB0_833
	s_ashr_i32 s11, s10, 31
	v_readlane_b32 s64, v250, 14
	v_readlane_b32 s65, v250, 15
	v_lshl_add_u64 v[156:157], s[10:11], 1, v[168:169]
	v_readlane_b32 s53, v250, 3
	v_mov_b64_e32 v[158:159], s[64:65]
	v_mad_u64_u32 v[158:159], s[44:45], v156, s71, v[158:159]
	v_mad_i32_i24 v159, v157, s71, v159
	v_lshl_add_u64 v[156:157], v[174:175], 2, v[158:159]
	global_load_dwordx4 v[156:159], v[156:157], off
	s_waitcnt vmcnt(0)

; template <int CTRL> DI float dpp_ror(float v) { return __builtin_bit_cast(float, __builtin_amdgcn_update_dpp(0, __builtin_bit_cast(int, v), CTRL, 0xf, 0xf, false)); }
;     template <int GV>
;     DI void conv_cols(const Acc& acc, const Unit& u, int ai, int n, int G, int f, int fr, const float (&rs)[4], bool samp, int sb, const f32x4 (&cw)[4], f32x4 (&cg)[4], bf16_t* actp) const {
;     ...
;         for (int m = 0; m < 4; ++m) X[m] = acc[ai][GV][m][n] * rs[m];
;         f32x4 Hh = (f32x4){0.f, 0.f, 0.f, 0.f};
;         if (samp) { if (fr >= 14) Hh = *(const f32x4*)(sconv + ((size_t)sb * 2 + (fr - 14)) * FF2 + GV * FF + f); }
;         else {
;             float* rw = RAW + ((((size_t)u.pm * 4 + G) * 4) * 2 + GV) * FF + f;
;             if (fr < 2 || fr >= 14) *(f32x4*)(rw + (size_t)(fr < 2 ? fr : fr - 12) * 2 * FF) = (fr < 2) ? X[0] : X[3];
;         }
;         if (fr >= 14) {
;             if (samp) *(f32x4*)(out + O_CONV_S + ((size_t)sb * 2 + (fr - 14)) * FF2 + GV * FF + f) = X[3];
;             else if ((u.pm & 31) == 31 && G == 3) *(f32x4*)(out + O_CONV_P + ((size_t)(u.pm >> 5) * 2 + (fr - 14)) * FF2 + GV * FF + f) = X[3];
;         }
; #pragma unroll
;         for (int m = 0; m < 4; ++m) {
;             f32x4 p1, p2;
; #pragma unroll
;             for (int j = 0; j < 4; ++j) {
;                 const float prev = (m == 0) ? Hh[j] : X[m - 1][j];
;                 const float a1 = dpp_ror<0x121>(X[m][j]), b1 = dpp_ror<0x121>(prev);
;                 const float a2 = dpp_ror<0x122>(X[m][j]), b2 = dpp_ror<0x122>(prev);
;                 p1[j] = (fr >= 1) ? a1 : b1; p2[j] = (fr >= 2) ? a2 : b2;
;     DI void operator()(const Acc& acc, const Unit& u, int wr, int wc, int fr, int fq) const {
;     ...
;             for (int m = 0; m < 4; ++m) rs[ai][m] = rsqrtf(ssl[wr * 64 + fr + ai * 128 + m * 16] * (1.0f / DM) + EPS);
.LBB0_839:
	s_or_b64 exec, exec, s[6:7]
	v_fmamk_f32 v178, v179, 0x3a000000, v200
	v_mul_f32_e32 v179, 0x4b800000, v178
	v_cmp_gt_f32_e32 vcc, s24, v178
	v_mov_b32_e32 v185, v184
	v_mov_b32_e32 v235, v169
	v_cndmask_b32_e32 v178, v178, v179, vcc
	v_fmamk_f32 v179, v180, 0x3a000000, v200
	v_mul_f32_e32 v180, 0x4b800000, v179
	v_cmp_gt_f32_e64 s[44:45], s24, v179
	v_rsq_f32_e32 v178, v178
	v_mov_b32_e32 v236, v169
	v_cndmask_b32_e64 v179, v179, v180, s[44:45]
	v_rsq_f32_e32 v179, v179
	v_mul_f32_e32 v180, 0x45800000, v178
	v_cndmask_b32_e32 v178, v178, v180, vcc
	v_mul_f32_e32 v180, 0x45800000, v179
	v_cndmask_b32_e64 v180, v179, v180, s[44:45]
	v_pk_mul_f32 v[194:195], v[150:151], v[178:179] op_sel_hi:[1,0]
	v_mov_b32_e32 v150, v184
	v_mov_b32_e32 v151, v184
	v_mov_b32_e32 v183, v182
	v_pk_mul_f32 v[146:147], v[146:147], v[180:181] op_sel_hi:[1,0]
	v_pk_mul_f32 v[144:145], v[144:145], v[180:181] op_sel_hi:[1,0]
	v_pk_mul_f32 v[148:149], v[148:149], v[178:179] op_sel_hi:[1,0]
	v_mov_b32_dpp v235, v156 row_ror:1 row_mask:0xf bank_mask:0xf
	v_mov_b32_dpp v236, v156 row_ror:2 row_mask:0xf bank_mask:0xf
	v_mov_b32_dpp v237, v157 row_ror:1 row_mask:0xf bank_mask:0xf
	v_mov_b32_dpp v238, v157 row_ror:2 row_mask:0xf bank_mask:0xf
	v_mov_b32_dpp v239, v158 row_ror:1 row_mask:0xf bank_mask:0xf
	v_mov_b32_dpp v240, v158 row_ror:2 row_mask:0xf bank_mask:0xf
	v_mov_b32_dpp v241, v159 row_ror:1 row_mask:0xf bank_mask:0xf
	v_mov_b32_dpp v242, v159 row_ror:2 row_mask:0xf bank_mask:0xf
	v_pk_mul_f32 v[156:157], v[142:143], v[150:151]
	v_pk_mul_f32 v[150:151], v[140:141], v[184:185]
	v_mov_b32_e32 v140, v182
	v_mov_b32_e32 v141, v182
	v_mov_b32_dpp v204, v192 row_ror:1 row_mask:0xf bank_mask:0xf
	v_mov_b32_dpp v209, v192 row_ror:2 row_mask:0xf bank_mask:0xf
	v_mov_b32_dpp v213, v193 row_ror:1 row_mask:0xf bank_mask:0xf
	v_mov_b32_dpp v216, v193 row_ror:2 row_mask:0xf bank_mask:0xf
	v_mov_b32_dpp v219, v190 row_ror:1 row_mask:0xf bank_mask:0xf
	v_mov_b32_dpp v223, v190 row_ror:2 row_mask:0xf bank_mask:0xf
	v_mov_b32_dpp v227, v191 row_ror:1 row_mask:0xf bank_mask:0xf
	v_mov_b32_dpp v231, v191 row_ror:2 row_mask:0xf bank_mask:0xf
	v_mov_b32_dpp v158, v148 row_ror:1 row_mask:0xf bank_mask:0xf
	v_mov_b32_dpp v159, v148 row_ror:2 row_mask:0xf bank_mask:0xf
	v_mov_b32_dpp v217, v149 row_ror:1 row_mask:0xf bank_mask:0xf
	v_mov_b32_dpp v218, v149 row_ror:2 row_mask:0xf bank_mask:0xf
	v_mov_b32_dpp v220, v194 row_ror:1 row_mask:0xf bank_mask:0xf
	v_mov_b32_dpp v221, v194 row_ror:2 row_mask:0xf bank_mask:0xf
	v_mov_b32_dpp v222, v195 row_ror:1 row_mask:0xf bank_mask:0xf
	v_mov_b32_dpp v224, v195 row_ror:2 row_mask:0xf bank_mask:0xf
	v_mov_b32_dpp v205, v144 row_ror:1 row_mask:0xf bank_mask:0xf
	v_mov_b32_dpp v207, v144 row_ror:2 row_mask:0xf bank_mask:0xf
	v_mov_b32_dpp v208, v145 row_ror:1 row_mask:0xf bank_mask:0xf
	v_mov_b32_dpp v210, v145 row_ror:2 row_mask:0xf bank_mask:0xf
	v_mov_b32_dpp v211, v146 row_ror:1 row_mask:0xf bank_mask:0xf
	v_mov_b32_dpp v212, v146 row_ror:2 row_mask:0xf bank_mask:0xf
	v_mov_b32_dpp v214, v147 row_ror:1 row_mask:0xf bank_mask:0xf
	v_mov_b32_dpp v215, v147 row_ror:2 row_mask:0xf bank_mask:0xf
	v_mov_b32_dpp v225, v152 row_ror:1 row_mask:0xf bank_mask:0xf
	v_mov_b32_dpp v226, v152 row_ror:2 row_mask:0xf bank_mask:0xf
	v_mov_b32_dpp v228, v153 row_ror:1 row_mask:0xf bank_mask:0xf
	v_mov_b32_dpp v229, v153 row_ror:2 row_mask:0xf bank_mask:0xf
	v_mov_b32_dpp v230, v154 row_ror:1 row_mask:0xf bank_mask:0xf
	v_mov_b32_dpp v232, v154 row_ror:2 row_mask:0xf bank_mask:0xf
	v_mov_b32_dpp v233, v155 row_ror:1 row_mask:0xf bank_mask:0xf
	v_mov_b32_dpp v234, v155 row_ror:2 row_mask:0xf bank_mask:0xf
	v_pk_mul_f32 v[138:139], v[138:139], v[140:141]
	v_pk_mul_f32 v[136:137], v[136:137], v[182:183]
	s_mov_b64 s[6:7], -1
	s_and_b64 vcc, exec, s[4:5]
	s_cbranch_vccz .LBB0_843
	s_and_saveexec_b64 s[4:5], s[14:15]
	s_cbranch_execz .LBB0_842
	s_add_u32 s6, s80, s31
	s_addc_u32 s7, s81, s8
	v_lshl_add_u64 v[140:141], v[174:175], 2, s[6:7]
	v_lshl_add_u64 v[244:245], v[140:141], 0, v[176:177]
	v_add_co_u32_e32 v244, vcc, 0x5000, v244
	v_cndmask_b32_e64 v143, v139, v157, s[16:17]
	v_cndmask_b32_e64 v142, v138, v156, s[16:17]
	v_cndmask_b32_e64 v141, v137, v151, s[16:17]
	v_cndmask_b32_e64 v140, v136, v150, s[16:17]
	v_addc_co_u32_e32 v245, vcc, 0, v245, vcc
	global_store_dwordx4 v[244:245], v[140:143], off offset:2048

;     template <int GV>
;     DI void conv_cols(const Acc& acc, const Unit& u, int ai, int n, int G, int f, int fr, const float (&rs)[4], bool samp, int sb, const f32x4 (&cw)[4], f32x4 (&cg)[4], bf16_t* actp) const {
;     ...
;         if (samp) { if (fr >= 14) Hh = *(const f32x4*)(sconv + ((size_t)sb * 2 + (fr - 14)) * FF2 + GV * FF + f); }
.LBB0_843:
	v_mov_b32_e32 v140, 0
	s_andn2_b64 vcc, exec, s[6:7]
	v_mov_b32_e32 v141, 0
	v_mov_b32_e32 v142, 0
	v_mov_b32_e32 v143, 0
	s_cbranch_vccnz .LBB0_847
	v_mov_b32_e32 v143, 0
	v_mov_b32_e32 v142, 0
	v_mov_b32_e32 v141, 0
	v_mov_b32_e32 v140, 0
	s_and_saveexec_b64 s[4:5], s[42:43]
	s_cbranch_execz .LBB0_846
	s_ashr_i32 s11, s10, 31
	v_readlane_b32 s60, v250, 14
	v_readlane_b32 s61, v250, 15
	v_lshl_add_u64 v[140:141], s[10:11], 1, v[168:169]
	v_readlane_b32 s49, v250, 3
	v_mov_b64_e32 v[142:143], s[60:61]
	v_mad_u64_u32 v[142:143], s[6:7], v140, s71, v[142:143]
	v_mad_i32_i24 v143, v141, s71, v143
	v_lshl_add_u64 v[140:141], v[174:175], 2, v[142:143]
	v_add_co_u32_e32 v140, vcc, 0x5000, v140
	v_readlane_b32 s50, v250, 4
	s_nop 0
	v_addc_co_u32_e32 v141, vcc, 0, v141, vcc
	global_load_dwordx4 v[140:143], v[140:141], off offset:2048
	s_waitcnt vmcnt(0)

; DI unsigned cvtpk(float lo, float hi) { f32x2_t v = {lo, hi}; bf16x2_t b = __builtin_convertvector(v, bf16x2_t); return __builtin_bit_cast(unsigned, b); }
; DI float silu_f(float x) { return x * frcp(1.f + fexp2(-x * LOG2E)); }
; template <int CTRL> DI float dpp_ror(float v) { return __builtin_bit_cast(float, __builtin_amdgcn_update_dpp(0, __builtin_bit_cast(int, v), CTRL, 0xf, 0xf, false)); }
;     template <int GV>
;     DI void conv_cols(const Acc& acc, const Unit& u, int ai, int n, int G, int f, int fr, const float (&rs)[4], bool samp, int sb, const f32x4 (&cw)[4], f32x4 (&cg)[4], bf16_t* actp) const {
;     ...
;         for (int m = 0; m < 4; ++m) {
;             f32x4 p1, p2;
; #pragma unroll
;             for (int j = 0; j < 4; ++j) {
;                 const float prev = (m == 0) ? Hh[j] : X[m - 1][j];
;                 const float a1 = dpp_ror<0x121>(X[m][j]), b1 = dpp_ror<0x121>(prev);
;                 const float a2 = dpp_ror<0x122>(X[m][j]), b2 = dpp_ror<0x122>(prev);
;                 p1[j] = (fr >= 1) ? a1 : b1; p2[j] = (fr >= 2) ? a2 : b2;
;             }
;             const f32x4 c = cw[3] + cw[0] * p2 + cw[1] * p1 + cw[2] * X[m];
;             if (GV == 0) cg[m] = c;
;             else { u32x2 wv; wv.x = cvtpk(silu_f(cg[m][0]) * c[0], silu_f(cg[m][1]) * c[1]); wv.y = cvtpk(silu_f(cg[m][2]) * c[2], silu_f(cg[m][3]) * c[3]);
;                 *(u32x2*)(actp + (size_t)(m * 16) * FFP) = wv; }
;     DI void operator()(const Acc& acc, const Unit& u, int wr, int wc, int fr, int fq) const {
;     ...
;             for (int m = 0; m < 4; ++m) rs[ai][m] = rsqrtf(ssl[wr * 64 + fr + ai * 128 + m * 16] * (1.0f / DM) + EPS);
.LBB0_852:
	s_or_b64 exec, exec, s[4:5]
	s_lshl_b32 s4, s0, 8
	v_readlane_b32 s0, v249, 7
	s_add_i32 s4, s4, s0
	v_cmp_lt_i32_e64 s[0:1], 0, v203
	v_cmp_lt_i32_e64 s[2:3], 1, v203
	v_add_u32_e32 v202, s4, v203
	v_cndmask_b32_e64 v245, v237, v213, s[0:1]
	v_cndmask_b32_e64 v236, v236, v209, s[2:3]
	v_cndmask_b32_e64 v237, v238, v216, s[2:3]
	v_cndmask_b32_e64 v244, v235, v204, s[0:1]
	v_cndmask_b32_e64 v238, v239, v219, s[0:1]
	v_cndmask_b32_e64 v240, v240, v223, s[2:3]
	v_cndmask_b32_e64 v239, v241, v227, s[0:1]
	v_cndmask_b32_e64 v241, v242, v231, s[2:3]
	s_waitcnt lgkmcnt(1)
	v_pk_fma_f32 v[236:237], v[116:117], v[236:237], v[124:125]
	v_pk_fma_f32 v[240:241], v[118:119], v[240:241], v[126:127]
	v_pk_fma_f32 v[236:237], v[112:113], v[244:245], v[236:237]
	v_pk_fma_f32 v[238:239], v[114:115], v[238:239], v[240:241]
	v_pk_fma_f32 v[236:237], v[192:193], v[120:121], v[236:237]
	v_cndmask_b32_e64 v192, v209, v159, s[2:3]
	v_cndmask_b32_e64 v193, v216, v218, s[2:3]
	v_cndmask_b32_e64 v242, v223, v221, s[2:3]
	v_cndmask_b32_e64 v243, v231, v224, s[2:3]
	v_pk_fma_f32 v[238:239], v[190:191], v[122:123], v[238:239]
	v_cndmask_b32_e64 v190, v204, v158, s[0:1]
	v_cndmask_b32_e64 v191, v213, v217, s[0:1]
	v_cndmask_b32_e64 v240, v219, v220, s[0:1]
	v_cndmask_b32_e64 v241, v227, v222, s[0:1]
	v_pk_fma_f32 v[242:243], v[118:119], v[242:243], v[126:127]
	v_pk_fma_f32 v[192:193], v[116:117], v[192:193], v[124:125]
	v_cndmask_b32_e64 v216, v221, v212, s[2:3]
	v_pk_fma_f32 v[190:191], v[112:113], v[190:191], v[192:193]
	v_pk_fma_f32 v[192:193], v[114:115], v[240:241], v[242:243]
	v_cndmask_b32_e64 v204, v212, v232, s[2:3]
	v_pk_fma_f32 v[192:193], v[194:195], v[122:123], v[192:193]
	v_pk_fma_f32 v[194:195], v[148:149], v[120:121], v[190:191]
	v_cndmask_b32_e64 v148, v158, v205, s[0:1]
	v_cndmask_b32_e64 v158, v159, v207, s[2:3]
	v_cndmask_b32_e64 v149, v217, v208, s[0:1]
	v_cndmask_b32_e64 v159, v218, v210, s[2:3]
	v_cndmask_b32_e64 v217, v224, v215, s[2:3]
	v_cndmask_b32_e64 v190, v220, v211, s[0:1]
	v_cndmask_b32_e64 v191, v222, v214, s[0:1]
	v_pk_fma_f32 v[216:217], v[118:119], v[216:217], v[126:127]
	v_pk_fma_f32 v[158:159], v[116:117], v[158:159], v[124:125]
	v_readlane_b32 s4, v249, 21
	v_pk_fma_f32 v[148:149], v[112:113], v[148:149], v[158:159]
	v_pk_fma_f32 v[158:159], v[114:115], v[190:191], v[216:217]
	v_pk_fma_f32 v[190:191], v[120:121], v[144:145], v[148:149]
	v_pk_fma_f32 v[158:159], v[122:123], v[146:147], v[158:159]
	v_cndmask_b32_e64 v144, v205, v225, s[0:1]
	v_cndmask_b32_e64 v146, v207, v226, s[2:3]
	v_cndmask_b32_e64 v147, v210, v229, s[2:3]
	v_cndmask_b32_e64 v205, v215, v234, s[2:3]
	v_cndmask_b32_e64 v145, v208, v228, s[0:1]
	v_cndmask_b32_e64 v148, v211, v230, s[0:1]
	v_cndmask_b32_e64 v149, v214, v233, s[0:1]
	v_pk_fma_f32 v[204:205], v[118:119], v[204:205], v[126:127]
	v_pk_fma_f32 v[146:147], v[116:117], v[146:147], v[124:125]
	v_readlane_b32 s5, v249, 22
	v_pk_fma_f32 v[144:145], v[112:113], v[144:145], v[146:147]
	v_pk_fma_f32 v[146:147], v[114:115], v[148:149], v[204:205]
	v_pk_fma_f32 v[152:153], v[120:121], v[152:153], v[144:145]
	v_pk_fma_f32 v[154:155], v[122:123], v[154:155], v[146:147]
	v_fmamk_f32 v146, v188, 0x3a000000, v200
	v_mul_f32_e32 v147, 0x4b800000, v146
	v_cmp_gt_f32_e32 vcc, s24, v146
	v_mov_b64_e32 v[144:145], s[4:5]
	v_mad_i64_i32 v[144:145], s[4:5], v202, s72, v[144:145]
	v_cndmask_b32_e32 v146, v146, v147, vcc
	v_fmamk_f32 v147, v187, 0x3a000000, v200
	v_mul_f32_e32 v148, 0x4b800000, v147
	v_cmp_gt_f32_e64 s[54:55], s24, v147
	v_rsq_f32_e32 v146, v146
	v_mov_b32_e32 v204, v180
	v_cndmask_b32_e64 v147, v147, v148, s[54:55]
	v_rsq_f32_e32 v147, v147
	v_lshl_add_u64 v[148:149], v[174:175], 1, v[144:145]
	v_mul_f32_e32 v144, 0x45800000, v146
	v_cndmask_b32_e32 v146, v146, v144, vcc
	v_mul_f32_e32 v144, 0x45800000, v147
	v_cndmask_b32_e64 v144, v147, v144, s[54:55]
	v_mov_b32_e32 v205, v180
	v_pk_mul_f32 v[130:131], v[130:131], v[204:205]
	v_mov_b32_e32 v204, v178
	v_mov_b32_e32 v205, v178
	v_mov_b32_dpp v145, v150 row_ror:1 row_mask:0xf bank_mask:0xf
	v_mov_b32_dpp v147, v140 row_ror:1 row_mask:0xf bank_mask:0xf
	v_mov_b32_dpp v187, v150 row_ror:2 row_mask:0xf bank_mask:0xf
	v_mov_b32_dpp v188, v140 row_ror:2 row_mask:0xf bank_mask:0xf
	v_pk_mul_f32 v[134:135], v[134:135], v[204:205]
	v_cndmask_b32_e64 v140, v147, v145, s[0:1]
	v_cndmask_b32_e64 v204, v188, v187, s[2:3]
	v_mov_b32_dpp v147, v151 row_ror:1 row_mask:0xf bank_mask:0xf
	v_mov_b32_dpp v188, v141 row_ror:1 row_mask:0xf bank_mask:0xf
	v_mov_b32_dpp v205, v141 row_ror:2 row_mask:0xf bank_mask:0xf
	v_cndmask_b32_e64 v141, v188, v147, s[0:1]
	v_mov_b32_dpp v188, v156 row_ror:1 row_mask:0xf bank_mask:0xf
	v_mov_b32_dpp v207, v142 row_ror:1 row_mask:0xf bank_mask:0xf
	v_mov_b32_dpp v208, v142 row_ror:2 row_mask:0xf bank_mask:0xf
	v_cndmask_b32_e64 v142, v207, v188, s[0:1]
	v_mov_b32_dpp v210, v156 row_ror:2 row_mask:0xf bank_mask:0xf
	v_mov_b32_dpp v207, v157 row_ror:1 row_mask:0xf bank_mask:0xf
	v_mov_b32_dpp v209, v143 row_ror:1 row_mask:0xf bank_mask:0xf
	v_mov_b32_dpp v211, v157 row_ror:2 row_mask:0xf bank_mask:0xf
	v_mov_b32_dpp v212, v143 row_ror:2 row_mask:0xf bank_mask:0xf
	v_cndmask_b32_e64 v208, v208, v210, s[2:3]
	v_cndmask_b32_e64 v143, v209, v207, s[0:1]
	v_cndmask_b32_e64 v209, v212, v211, s[2:3]
	s_waitcnt lgkmcnt(0)
; DI unsigned cvtpk(float lo, float hi) { f32x2_t v = {lo, hi}; bf16x2_t b = __builtin_convertvector(v, bf16x2_t); return __builtin_bit_cast(unsigned, b); }
; DI float silu_f(float x) { return x * frcp(1.f + fexp2(-x * LOG2E)); }
; template <int CTRL> DI float dpp_ror(float v) { return __builtin_bit_cast(float, __builtin_amdgcn_update_dpp(0, __builtin_bit_cast(int, v), CTRL, 0xf, 0xf, false)); }
;     template <int GV>
;     DI void conv_cols(const Acc& acc, const Unit& u, int ai, int n, int G, int f, int fr, const float (&rs)[4], bool samp, int sb, const f32x4 (&cw)[4], f32x4 (&cg)[4], bf16_t* actp) const {
;     ...
;         for (int m = 0; m < 4; ++m) {
;             f32x4 p1, p2;
; #pragma unroll
;             for (int j = 0; j < 4; ++j) {
;                 const float prev = (m == 0) ? Hh[j] : X[m - 1][j];
;                 const float a1 = dpp_ror<0x121>(X[m][j]), b1 = dpp_ror<0x121>(prev);
;                 const float a2 = dpp_ror<0x122>(X[m][j]), b2 = dpp_ror<0x122>(prev);
;                 p1[j] = (fr >= 1) ? a1 : b1; p2[j] = (fr >= 2) ? a2 : b2;
;             }
;             const f32x4 c = cw[3] + cw[0] * p2 + cw[1] * p1 + cw[2] * X[m];
;             if (GV == 0) cg[m] = c;
;             else { u32x2 wv; wv.x = cvtpk(silu_f(cg[m][0]) * c[0], silu_f(cg[m][1]) * c[1]); wv.y = cvtpk(silu_f(cg[m][2]) * c[2], silu_f(cg[m][3]) * c[3]);
;                 *(u32x2*)(actp + (size_t)(m * 16) * FFP) = wv; }
	v_pk_fma_f32 v[208:209], v[106:107], v[208:209], v[110:111]
	v_pk_fma_f32 v[142:143], v[102:103], v[142:143], v[208:209]
	v_mov_b32_e32 v179, v178
	v_pk_fma_f32 v[142:143], v[156:157], v[98:99], v[142:143]
	v_mul_f32_e32 v156, 0xbfb8aa3b, v236
	v_mul_f32_e32 v157, 0xbfb8aa3b, v237
	v_mov_b32_dpp v203, v151 row_ror:2 row_mask:0xf bank_mask:0xf
	v_exp_f32_e32 v156, v156
	v_exp_f32_e32 v157, v157
	v_cndmask_b32_e64 v205, v205, v203, s[2:3]
	v_pk_fma_f32 v[204:205], v[104:105], v[204:205], v[108:109]
	v_pk_mul_f32 v[132:133], v[132:133], v[178:179]
	v_pk_fma_f32 v[140:141], v[100:101], v[140:141], v[204:205]
	v_pk_fma_f32 v[140:141], v[150:151], v[96:97], v[140:141]
	v_add_f32_e32 v150, 1.0, v156
	v_add_f32_e32 v151, 1.0, v157
	v_mul_f32_e32 v156, 0xbfb8aa3b, v238
	v_mul_f32_e32 v157, 0xbfb8aa3b, v239
	v_exp_f32_e32 v156, v156
	v_exp_f32_e32 v157, v157
	v_rcp_f32_e32 v150, v150
	v_rcp_f32_e32 v151, v151
	v_add_f32_e32 v156, 1.0, v156
	v_add_f32_e32 v157, 1.0, v157
	v_rcp_f32_e32 v156, v156
	v_rcp_f32_e32 v157, v157
	v_pk_mul_f32 v[150:151], v[236:237], v[150:151]
	v_mov_b32_dpp v204, v132 row_ror:1 row_mask:0xf bank_mask:0xf
	v_pk_mul_f32 v[140:141], v[150:151], v[140:141]
	v_pk_mul_f32 v[150:151], v[238:239], v[156:157]
	v_cvt_pk_bf16_f32 v140, v140, v141
	v_pk_mul_f32 v[142:143], v[150:151], v[142:143]
	v_cvt_pk_bf16_f32 v141, v142, v143
	global_store_dwordx2 v[148:149], v[140:141], off
	v_mov_b32_dpp v205, v132 row_ror:2 row_mask:0xf bank_mask:0xf
	v_cndmask_b32_e64 v140, v145, v204, s[0:1]
	v_cndmask_b32_e64 v142, v187, v205, s[2:3]
	v_mov_b32_dpp v145, v133 row_ror:1 row_mask:0xf bank_mask:0xf
	v_cndmask_b32_e64 v141, v147, v145, s[0:1]
	v_mov_b32_dpp v187, v133 row_ror:2 row_mask:0xf bank_mask:0xf
	v_cndmask_b32_e64 v143, v203, v187, s[2:3]
	v_mov_b32_dpp v147, v134 row_ror:1 row_mask:0xf bank_mask:0xf
	v_mov_b32_dpp v203, v134 row_ror:2 row_mask:0xf bank_mask:0xf
	v_cndmask_b32_e64 v150, v188, v147, s[0:1]
	v_mov_b32_dpp v208, v135 row_ror:2 row_mask:0xf bank_mask:0xf
	v_pk_fma_f32 v[142:143], v[104:105], v[142:143], v[108:109]
	v_cndmask_b32_e64 v156, v210, v203, s[2:3]
	v_mov_b32_dpp v188, v135 row_ror:1 row_mask:0xf bank_mask:0xf
	v_cndmask_b32_e64 v157, v211, v208, s[2:3]
	v_pk_fma_f32 v[140:141], v[100:101], v[140:141], v[142:143]
	v_cndmask_b32_e64 v151, v207, v188, s[0:1]
	v_pk_fma_f32 v[156:157], v[106:107], v[156:157], v[110:111]
	v_pk_fma_f32 v[132:133], v[132:133], v[96:97], v[140:141]
	v_mul_f32_e32 v140, 0xbfb8aa3b, v194
	v_mul_f32_e32 v141, 0xbfb8aa3b, v195
	v_pk_fma_f32 v[142:143], v[102:103], v[150:151], v[156:157]
	v_exp_f32_e32 v140, v140
	v_exp_f32_e32 v141, v141
	v_pk_fma_f32 v[134:135], v[134:135], v[98:99], v[142:143]
	v_mul_f32_e32 v142, 0xbfb8aa3b, v192
	v_mul_f32_e32 v143, 0xbfb8aa3b, v193
	v_exp_f32_e32 v142, v142
	v_exp_f32_e32 v143, v143
	v_add_f32_e32 v140, 1.0, v140
	v_add_f32_e32 v141, 1.0, v141
	v_rcp_f32_e32 v140, v140
	v_rcp_f32_e32 v141, v141
	v_add_f32_e32 v142, 1.0, v142
	v_add_f32_e32 v143, 1.0, v143
	v_rcp_f32_e32 v142, v142
	v_rcp_f32_e32 v143, v143
	v_pk_mul_f32 v[140:141], v[194:195], v[140:141]
	v_mov_b32_e32 v181, v180
	v_pk_mul_f32 v[132:133], v[140:141], v[132:133]
	v_pk_mul_f32 v[128:129], v[128:129], v[180:181]
	v_cvt_pk_bf16_f32 v140, v132, v133
	v_pk_mul_f32 v[132:133], v[192:193], v[142:143]
	v_pk_mul_f32 v[132:133], v[132:133], v[134:135]
	v_cvt_pk_bf16_f32 v141, v132, v133
	v_add_co_u32_e32 v132, vcc, s77, v148
	v_mov_b32_dpp v192, v129 row_ror:1 row_mask:0xf bank_mask:0xf
	s_nop 0
	v_addc_co_u32_e32 v133, vcc, 0, v149, vcc
	v_mov_b32_dpp v193, v129 row_ror:2 row_mask:0xf bank_mask:0xf
	v_cndmask_b32_e64 v135, v145, v192, s[0:1]
	global_store_dwordx2 v[132:133], v[140:141], off offset:2048
	v_cndmask_b32_e64 v141, v187, v193, s[2:3]
	v_mov_b32_dpp v145, v130 row_ror:1 row_mask:0xf bank_mask:0xf
	v_mov_b32_dpp v157, v128 row_ror:2 row_mask:0xf bank_mask:0xf
	v_mov_b32_dpp v187, v130 row_ror:2 row_mask:0xf bank_mask:0xf
	v_cndmask_b32_e64 v142, v147, v145, s[0:1]
	v_mov_b32_dpp v194, v131 row_ror:2 row_mask:0xf bank_mask:0xf
	v_mov_b32_dpp v156, v128 row_ror:1 row_mask:0xf bank_mask:0xf
	v_cndmask_b32_e64 v140, v205, v157, s[2:3]
	v_cndmask_b32_e64 v150, v203, v187, s[2:3]
	v_mov_b32_dpp v147, v131 row_ror:1 row_mask:0xf bank_mask:0xf
; DI unsigned cvtpk(float lo, float hi) { f32x2_t v = {lo, hi}; bf16x2_t b = __builtin_convertvector(v, bf16x2_t); return __builtin_bit_cast(unsigned, b); }
; DI float silu_f(float x) { return x * frcp(1.f + fexp2(-x * LOG2E)); }
; template <int CTRL> DI float dpp_ror(float v) { return __builtin_bit_cast(float, __builtin_amdgcn_update_dpp(0, __builtin_bit_cast(int, v), CTRL, 0xf, 0xf, false)); }
;     template <int GV>
;     DI void conv_cols(const Acc& acc, const Unit& u, int ai, int n, int G, int f, int fr, const float (&rs)[4], bool samp, int sb, const f32x4 (&cw)[4], f32x4 (&cg)[4], bf16_t* actp) const {
;     ...
;             if (fr < 2 || fr >= 14) *(f32x4*)(rw + (size_t)(fr < 2 ? fr : fr - 12) * 2 * FF) = (fr < 2) ? X[0] : X[3];
;         }
;         if (fr >= 14) {
;             if (samp) *(f32x4*)(out + O_CONV_S + ((size_t)sb * 2 + (fr - 14)) * FF2 + GV * FF + f) = X[3];
;             else if ((u.pm & 31) == 31 && G == 3) *(f32x4*)(out + O_CONV_P + ((size_t)(u.pm >> 5) * 2 + (fr - 14)) * FF2 + GV * FF + f) = X[3];
;         }
; #pragma unroll
;         for (int m = 0; m < 4; ++m) {
;             f32x4 p1, p2;
; #pragma unroll
;             for (int j = 0; j < 4; ++j) {
;                 const float prev = (m == 0) ? Hh[j] : X[m - 1][j];
;                 const float a1 = dpp_ror<0x121>(X[m][j]), b1 = dpp_ror<0x121>(prev);
;                 const float a2 = dpp_ror<0x122>(X[m][j]), b2 = dpp_ror<0x122>(prev);
;                 p1[j] = (fr >= 1) ? a1 : b1; p2[j] = (fr >= 2) ? a2 : b2;
;             }
;             const f32x4 c = cw[3] + cw[0] * p2 + cw[1] * p1 + cw[2] * X[m];
;             if (GV == 0) cg[m] = c;
;             else { u32x2 wv; wv.x = cvtpk(silu_f(cg[m][0]) * c[0], silu_f(cg[m][1]) * c[1]); wv.y = cvtpk(silu_f(cg[m][2]) * c[2], silu_f(cg[m][3]) * c[3]);
;                 *(u32x2*)(actp + (size_t)(m * 16) * FFP) = wv; }
	v_cndmask_b32_e64 v151, v208, v194, s[2:3]
	v_cndmask_b32_e64 v134, v204, v156, s[0:1]
	v_cndmask_b32_e64 v143, v188, v147, s[0:1]
	v_pk_fma_f32 v[150:151], v[106:107], v[150:151], v[110:111]
	v_pk_fma_f32 v[140:141], v[104:105], v[140:141], v[108:109]
	v_pk_mul_f32 v[90:91], v[90:91], v[144:145] op_sel_hi:[1,0]
	v_pk_fma_f32 v[134:135], v[100:101], v[134:135], v[140:141]
	v_pk_fma_f32 v[140:141], v[102:103], v[142:143], v[150:151]
	v_pk_fma_f32 v[128:129], v[128:129], v[96:97], v[134:135]
	v_pk_fma_f32 v[130:131], v[130:131], v[98:99], v[140:141]
	v_mul_f32_e32 v140, 0xbfb8aa3b, v190
	v_mul_f32_e32 v141, 0xbfb8aa3b, v191
	v_exp_f32_e32 v140, v140
	v_exp_f32_e32 v141, v141
	v_pk_mul_f32 v[88:89], v[88:89], v[144:145] op_sel_hi:[1,0]
	v_add_f32_e32 v134, 1.0, v140
	v_add_f32_e32 v135, 1.0, v141
	v_mul_f32_e32 v140, 0xbfb8aa3b, v158
	v_mul_f32_e32 v141, 0xbfb8aa3b, v159
	v_exp_f32_e32 v140, v140
	v_exp_f32_e32 v141, v141
	v_rcp_f32_e32 v134, v134
	v_rcp_f32_e32 v135, v135
	v_add_f32_e32 v140, 1.0, v140
	v_add_f32_e32 v141, 1.0, v141
	v_rcp_f32_e32 v140, v140
	v_rcp_f32_e32 v141, v141
	v_pk_mul_f32 v[134:135], v[190:191], v[134:135]
	v_mov_b32_dpp v143, v139 row_ror:2 row_mask:0xf bank_mask:0xf
	v_pk_mul_f32 v[128:129], v[134:135], v[128:129]
	v_pk_mul_f32 v[134:135], v[158:159], v[140:141]
	v_cvt_pk_bf16_f32 v128, v128, v129
	v_pk_mul_f32 v[130:131], v[134:135], v[130:131]
	v_add_co_u32_e32 v134, vcc, s82, v148
	v_cvt_pk_bf16_f32 v129, v130, v131
	s_nop 0
	v_addc_co_u32_e32 v135, vcc, 0, v149, vcc
	global_store_dwordx2 v[134:135], v[128:129], off
	v_mov_b32_dpp v129, v136 row_ror:2 row_mask:0xf bank_mask:0xf
	v_cndmask_b32_e64 v130, v157, v129, s[2:3]
	v_mov_b32_dpp v131, v137 row_ror:2 row_mask:0xf bank_mask:0xf
	v_mov_b32_dpp v141, v138 row_ror:2 row_mask:0xf bank_mask:0xf
	v_mov_b32_dpp v128, v136 row_ror:1 row_mask:0xf bank_mask:0xf
	v_mov_b32_dpp v129, v137 row_ror:1 row_mask:0xf bank_mask:0xf
	v_cndmask_b32_e64 v131, v193, v131, s[2:3]
	v_cndmask_b32_e64 v142, v187, v141, s[2:3]
	v_cndmask_b32_e64 v128, v156, v128, s[0:1]
	v_cndmask_b32_e64 v129, v192, v129, s[0:1]
	v_mov_b32_dpp v140, v138 row_ror:1 row_mask:0xf bank_mask:0xf
	v_mov_b32_dpp v141, v139 row_ror:1 row_mask:0xf bank_mask:0xf
	v_cndmask_b32_e64 v143, v194, v143, s[2:3]
	v_pk_fma_f32 v[130:131], v[104:105], v[130:131], v[108:109]
	v_cndmask_b32_e64 v140, v145, v140, s[0:1]
	v_cndmask_b32_e64 v141, v147, v141, s[0:1]
	v_pk_fma_f32 v[142:143], v[106:107], v[142:143], v[110:111]
	v_pk_fma_f32 v[128:129], v[100:101], v[128:129], v[130:131]
	v_pk_fma_f32 v[130:131], v[102:103], v[140:141], v[142:143]
	v_pk_fma_f32 v[128:129], v[96:97], v[136:137], v[128:129]
	v_mul_f32_e32 v136, 0xbfb8aa3b, v152
	v_mul_f32_e32 v137, 0xbfb8aa3b, v153
	v_exp_f32_e32 v136, v136
	v_exp_f32_e32 v137, v137
	v_pk_fma_f32 v[130:131], v[98:99], v[138:139], v[130:131]
	v_mul_f32_e32 v138, 0xbfb8aa3b, v154
	v_mul_f32_e32 v139, 0xbfb8aa3b, v155
	v_exp_f32_e32 v138, v138
	v_exp_f32_e32 v139, v139
	v_add_f32_e32 v136, 1.0, v136
	v_add_f32_e32 v137, 1.0, v137
	v_rcp_f32_e32 v136, v136
	v_rcp_f32_e32 v137, v137
	v_add_f32_e32 v138, 1.0, v138
	v_add_f32_e32 v139, 1.0, v139
	v_rcp_f32_e32 v138, v138
	v_rcp_f32_e32 v139, v139
	v_pk_mul_f32 v[136:137], v[152:153], v[136:137]
	v_pk_mul_f32 v[140:141], v[92:93], v[146:147] op_sel_hi:[1,0]
	v_pk_mul_f32 v[128:129], v[136:137], v[128:129]
	v_pk_mul_f32 v[136:137], v[154:155], v[138:139]
	v_cvt_pk_bf16_f32 v128, v128, v129
	v_pk_mul_f32 v[130:131], v[136:137], v[130:131]
	v_add_co_u32_e32 v136, vcc, s83, v148
	v_cvt_pk_bf16_f32 v129, v130, v131
	s_nop 0
	v_addc_co_u32_e32 v137, vcc, 0, v149, vcc
	v_pk_mul_f32 v[138:139], v[94:95], v[146:147] op_sel_hi:[1,0]
	s_and_b64 vcc, exec, s[66:67]
	s_mov_b64 s[4:5], -1
	global_store_dwordx2 v[136:137], v[128:129], off offset:2048
	s_cbranch_vccnz .LBB0_856
	s_and_saveexec_b64 s[4:5], s[14:15]
	s_cbranch_execz .LBB0_855
	s_add_u32 s6, s93, s31
	s_addc_u32 s7, s25, s8
	v_lshl_add_u64 v[92:93], v[174:175], 2, s[6:7]
	v_lshl_add_u64 v[128:129], v[92:93], 0, v[176:177]
	v_cndmask_b32_e64 v95, v91, v139, s[16:17]
	v_cndmask_b32_e64 v94, v90, v138, s[16:17]
	v_cndmask_b32_e64 v93, v89, v141, s[16:17]
	v_cndmask_b32_e64 v92, v88, v140, s[16:17]
	global_store_dwordx4 v[128:129], v[92:95], off

;     template <int GV>
;     DI void conv_cols(const Acc& acc, const Unit& u, int ai, int n, int G, int f, int fr, const float (&rs)[4], bool samp, int sb, const f32x4 (&cw)[4], f32x4 (&cg)[4], bf16_t* actp) const {
;     ...
;         if (samp) { if (fr >= 14) Hh = *(const f32x4*)(sconv + ((size_t)sb * 2 + (fr - 14)) * FF2 + GV * FF + f); }
.LBB0_856:
	s_add_i32 s20, s20, s78
	v_mov_b32_e32 v92, 0
	s_andn2_b64 vcc, exec, s[4:5]
	v_mov_b32_e32 v93, 0
	v_mov_b32_e32 v94, 0
	v_mov_b32_e32 v95, 0
	s_cbranch_vccnz .LBB0_860
	v_mov_b32_e32 v95, 0
	v_mov_b32_e32 v94, 0
	v_mov_b32_e32 v93, 0
	v_mov_b32_e32 v92, 0
	s_and_saveexec_b64 s[4:5], s[42:43]
	s_cbranch_execz .LBB0_859
	s_ashr_i32 s21, s20, 31
	v_readlane_b32 s60, v250, 14
	v_readlane_b32 s61, v250, 15
	v_lshl_add_u64 v[92:93], s[20:21], 1, v[168:169]
	v_readlane_b32 s49, v250, 3
	v_mov_b64_e32 v[94:95], s[60:61]
	v_mad_u64_u32 v[94:95], s[6:7], v92, s71, v[94:95]
	v_mad_i32_i24 v95, v93, s71, v95
	v_lshl_add_u64 v[92:93], v[174:175], 2, v[94:95]
	global_load_dwordx4 v[92:95], v[92:93], off
	s_waitcnt vmcnt(0)

; template <int CTRL> DI float dpp_ror(float v) { return __builtin_bit_cast(float, __builtin_amdgcn_update_dpp(0, __builtin_bit_cast(int, v), CTRL, 0xf, 0xf, false)); }
;     template <int GV>
;     DI void conv_cols(const Acc& acc, const Unit& u, int ai, int n, int G, int f, int fr, const float (&rs)[4], bool samp, int sb, const f32x4 (&cw)[4], f32x4 (&cg)[4], bf16_t* actp) const {
;     ...
;         for (int m = 0; m < 4; ++m) X[m] = acc[ai][GV][m][n] * rs[m];
;         f32x4 Hh = (f32x4){0.f, 0.f, 0.f, 0.f};
;         if (samp) { if (fr >= 14) Hh = *(const f32x4*)(sconv + ((size_t)sb * 2 + (fr - 14)) * FF2 + GV * FF + f); }
;         else {
;             float* rw = RAW + ((((size_t)u.pm * 4 + G) * 4) * 2 + GV) * FF + f;
;             if (fr < 2 || fr >= 14) *(f32x4*)(rw + (size_t)(fr < 2 ? fr : fr - 12) * 2 * FF) = (fr < 2) ? X[0] : X[3];
;         }
;         if (fr >= 14) {
;             if (samp) *(f32x4*)(out + O_CONV_S + ((size_t)sb * 2 + (fr - 14)) * FF2 + GV * FF + f) = X[3];
;             else if ((u.pm & 31) == 31 && G == 3) *(f32x4*)(out + O_CONV_P + ((size_t)(u.pm >> 5) * 2 + (fr - 14)) * FF2 + GV * FF + f) = X[3];
;         }
; #pragma unroll
;         for (int m = 0; m < 4; ++m) {
;             f32x4 p1, p2;
; #pragma unroll
;             for (int j = 0; j < 4; ++j) {
;                 const float prev = (m == 0) ? Hh[j] : X[m - 1][j];
;                 const float a1 = dpp_ror<0x121>(X[m][j]), b1 = dpp_ror<0x121>(prev);
;                 const float a2 = dpp_ror<0x122>(X[m][j]), b2 = dpp_ror<0x122>(prev);
;                 p1[j] = (fr >= 1) ? a1 : b1; p2[j] = (fr >= 2) ? a2 : b2;
.LBB0_865:
	s_or_b64 exec, exec, s[4:5]
	v_fmamk_f32 v128, v189, 0x3a000000, v200
	v_cmp_gt_f32_e32 vcc, s24, v128
	v_mul_f32_e32 v129, 0x4b800000, v128
	v_mov_b32_e32 v147, v146
	v_cndmask_b32_e32 v128, v128, v129, vcc
	v_rsq_f32_e32 v128, v128
	v_mov_b32_e32 v214, v169
	v_mov_b32_e32 v215, v169
	v_mov_b32_e32 v216, v169
	v_mul_f32_e32 v129, 0x45800000, v128
	v_cndmask_b32_e32 v128, v128, v129, vcc
	v_fmamk_f32 v129, v186, 0x3a000000, v200
	v_cmp_gt_f32_e32 vcc, s24, v129
	v_mul_f32_e32 v130, 0x4b800000, v129
	v_mov_b32_e32 v217, v169
	v_cndmask_b32_e32 v129, v129, v130, vcc
	v_rsq_f32_e32 v129, v129
	v_mov_b32_e32 v218, v169
	v_mov_b32_e32 v219, v169
	v_mov_b32_e32 v220, v169
	v_mul_f32_e32 v130, 0x45800000, v129
	v_cndmask_b32_e32 v130, v129, v130, vcc
	v_pk_mul_f32 v[150:151], v[80:81], v[130:131] op_sel_hi:[1,0]
	v_mov_b32_e32 v80, v146
	v_mov_b32_e32 v81, v146
	v_mov_b32_e32 v145, v144
	v_pk_mul_f32 v[142:143], v[82:83], v[130:131] op_sel_hi:[1,0]
	v_pk_mul_f32 v[86:87], v[86:87], v[128:129] op_sel_hi:[1,0]
	v_pk_mul_f32 v[84:85], v[84:85], v[128:129] op_sel_hi:[1,0]
	v_mov_b32_dpp v214, v92 row_ror:1 row_mask:0xf bank_mask:0xf
	v_mov_b32_dpp v215, v92 row_ror:2 row_mask:0xf bank_mask:0xf
	v_mov_b32_dpp v216, v93 row_ror:1 row_mask:0xf bank_mask:0xf
	v_mov_b32_dpp v217, v93 row_ror:2 row_mask:0xf bank_mask:0xf
	v_mov_b32_dpp v218, v94 row_ror:1 row_mask:0xf bank_mask:0xf
	v_mov_b32_dpp v219, v94 row_ror:2 row_mask:0xf bank_mask:0xf
	v_mov_b32_dpp v220, v95 row_ror:1 row_mask:0xf bank_mask:0xf
	v_mov_b32_dpp v221, v95 row_ror:2 row_mask:0xf bank_mask:0xf
	v_pk_mul_f32 v[82:83], v[78:79], v[80:81]
	v_pk_mul_f32 v[80:81], v[76:77], v[146:147]
	v_mov_b32_e32 v76, v144
	v_mov_b32_e32 v77, v144
	v_mov_b32_dpp v152, v140 row_ror:1 row_mask:0xf bank_mask:0xf
	v_mov_b32_dpp v156, v140 row_ror:2 row_mask:0xf bank_mask:0xf
	v_mov_b32_dpp v92, v141 row_ror:1 row_mask:0xf bank_mask:0xf
	v_mov_b32_dpp v188, v141 row_ror:2 row_mask:0xf bank_mask:0xf
	v_mov_b32_dpp v190, v138 row_ror:1 row_mask:0xf bank_mask:0xf
	v_mov_b32_dpp v194, v138 row_ror:2 row_mask:0xf bank_mask:0xf
	v_mov_b32_dpp v205, v139 row_ror:1 row_mask:0xf bank_mask:0xf
	v_mov_b32_dpp v210, v139 row_ror:2 row_mask:0xf bank_mask:0xf
	v_mov_b32_dpp v93, v84 row_ror:1 row_mask:0xf bank_mask:0xf
	v_mov_b32_dpp v94, v84 row_ror:2 row_mask:0xf bank_mask:0xf
	v_mov_b32_dpp v95, v85 row_ror:1 row_mask:0xf bank_mask:0xf
	v_mov_b32_dpp v189, v85 row_ror:2 row_mask:0xf bank_mask:0xf
	v_mov_b32_dpp v191, v86 row_ror:1 row_mask:0xf bank_mask:0xf
	v_mov_b32_dpp v192, v86 row_ror:2 row_mask:0xf bank_mask:0xf
	v_mov_b32_dpp v193, v87 row_ror:1 row_mask:0xf bank_mask:0xf
	v_mov_b32_dpp v195, v87 row_ror:2 row_mask:0xf bank_mask:0xf
	v_mov_b32_dpp v153, v150 row_ror:1 row_mask:0xf bank_mask:0xf
	v_mov_b32_dpp v154, v150 row_ror:2 row_mask:0xf bank_mask:0xf
	v_mov_b32_dpp v155, v151 row_ror:1 row_mask:0xf bank_mask:0xf
	v_mov_b32_dpp v157, v151 row_ror:2 row_mask:0xf bank_mask:0xf
	v_mov_b32_dpp v158, v142 row_ror:1 row_mask:0xf bank_mask:0xf
	v_mov_b32_dpp v159, v142 row_ror:2 row_mask:0xf bank_mask:0xf
	v_mov_b32_dpp v186, v143 row_ror:1 row_mask:0xf bank_mask:0xf
	v_mov_b32_dpp v187, v143 row_ror:2 row_mask:0xf bank_mask:0xf
	v_mov_b32_dpp v203, v88 row_ror:1 row_mask:0xf bank_mask:0xf
	v_mov_b32_dpp v204, v88 row_ror:2 row_mask:0xf bank_mask:0xf
	v_mov_b32_dpp v207, v89 row_ror:1 row_mask:0xf bank_mask:0xf
	v_mov_b32_dpp v208, v89 row_ror:2 row_mask:0xf bank_mask:0xf
	v_mov_b32_dpp v209, v90 row_ror:1 row_mask:0xf bank_mask:0xf
	v_mov_b32_dpp v211, v90 row_ror:2 row_mask:0xf bank_mask:0xf
	v_mov_b32_dpp v212, v91 row_ror:1 row_mask:0xf bank_mask:0xf
	v_mov_b32_dpp v213, v91 row_ror:2 row_mask:0xf bank_mask:0xf
	v_pk_mul_f32 v[74:75], v[74:75], v[76:77]
	v_pk_mul_f32 v[72:73], v[72:73], v[144:145]
	s_mov_b64 s[4:5], -1
	s_and_b64 vcc, exec, s[66:67]
	s_cbranch_vccnz .LBB0_869
	s_and_saveexec_b64 s[4:5], s[14:15]
	s_cbranch_execz .LBB0_868
	s_add_u32 s6, s93, s31
	s_addc_u32 s7, s25, s8
	v_lshl_add_u64 v[76:77], v[174:175], 2, s[6:7]
	v_lshl_add_u64 v[222:223], v[76:77], 0, v[176:177]
	v_add_co_u32_e32 v222, vcc, 0x5000, v222
	v_cndmask_b32_e64 v79, v75, v83, s[16:17]
	v_cndmask_b32_e64 v78, v74, v82, s[16:17]
	v_cndmask_b32_e64 v77, v73, v81, s[16:17]
	v_cndmask_b32_e64 v76, v72, v80, s[16:17]
	v_addc_co_u32_e32 v223, vcc, 0, v223, vcc
	global_store_dwordx4 v[222:223], v[76:79], off offset:2048

;     template <int GV>
;     DI void conv_cols(const Acc& acc, const Unit& u, int ai, int n, int G, int f, int fr, const float (&rs)[4], bool samp, int sb, const f32x4 (&cw)[4], f32x4 (&cg)[4], bf16_t* actp) const {
;     ...
;         if (samp) { if (fr >= 14) Hh = *(const f32x4*)(sconv + ((size_t)sb * 2 + (fr - 14)) * FF2 + GV * FF + f); }
.LBB0_869:
	v_mov_b32_e32 v76, 0
	s_andn2_b64 vcc, exec, s[4:5]
	v_mov_b32_e32 v77, 0
	v_mov_b32_e32 v78, 0
	v_mov_b32_e32 v79, 0
	s_cbranch_vccnz .LBB0_873
	v_mov_b32_e32 v79, 0
	v_mov_b32_e32 v78, 0
	v_mov_b32_e32 v77, 0
	v_mov_b32_e32 v76, 0
	s_and_saveexec_b64 s[4:5], s[42:43]
	s_cbranch_execz .LBB0_872
	s_ashr_i32 s21, s20, 31
	v_readlane_b32 s60, v250, 14
	v_readlane_b32 s61, v250, 15
	v_lshl_add_u64 v[76:77], s[20:21], 1, v[168:169]
	v_readlane_b32 s49, v250, 3
	v_mov_b64_e32 v[78:79], s[60:61]
	v_mad_u64_u32 v[78:79], s[6:7], v76, s71, v[78:79]
	v_mad_i32_i24 v79, v77, s71, v79
	v_lshl_add_u64 v[76:77], v[174:175], 2, v[78:79]
	v_add_co_u32_e32 v76, vcc, 0x5000, v76
	v_readlane_b32 s50, v250, 4
	s_nop 0
	v_addc_co_u32_e32 v77, vcc, 0, v77, vcc
	global_load_dwordx4 v[76:79], v[76:77], off offset:2048
	s_waitcnt vmcnt(0)

; DI unsigned cvtpk(float lo, float hi) { f32x2_t v = {lo, hi}; bf16x2_t b = __builtin_convertvector(v, bf16x2_t); return __builtin_bit_cast(unsigned, b); }
; DI float silu_f(float x) { return x * frcp(1.f + fexp2(-x * LOG2E)); }
; template <int CTRL> DI float dpp_ror(float v) { return __builtin_bit_cast(float, __builtin_amdgcn_update_dpp(0, __builtin_bit_cast(int, v), CTRL, 0xf, 0xf, false)); }
;     template <int GV>
;     DI void conv_cols(const Acc& acc, const Unit& u, int ai, int n, int G, int f, int fr, const float (&rs)[4], bool samp, int sb, const f32x4 (&cw)[4], f32x4 (&cg)[4], bf16_t* actp) const {
;     ...
;         for (int m = 0; m < 4; ++m) {
;             f32x4 p1, p2;
; #pragma unroll
;             for (int j = 0; j < 4; ++j) {
;                 const float prev = (m == 0) ? Hh[j] : X[m - 1][j];
;                 const float a1 = dpp_ror<0x121>(X[m][j]), b1 = dpp_ror<0x121>(prev);
;                 const float a2 = dpp_ror<0x122>(X[m][j]), b2 = dpp_ror<0x122>(prev);
;                 p1[j] = (fr >= 1) ? a1 : b1; p2[j] = (fr >= 2) ? a2 : b2;
;             }
;             const f32x4 c = cw[3] + cw[0] * p2 + cw[1] * p1 + cw[2] * X[m];
;             if (GV == 0) cg[m] = c;
;             else { u32x2 wv; wv.x = cvtpk(silu_f(cg[m][0]) * c[0], silu_f(cg[m][1]) * c[1]); wv.y = cvtpk(silu_f(cg[m][2]) * c[2], silu_f(cg[m][3]) * c[3]);
;                 *(u32x2*)(actp + (size_t)(m * 16) * FFP) = wv; }
.LBB0_878:
	s_or_b64 exec, exec, s[4:5]
	v_cndmask_b32_e64 v222, v215, v156, s[2:3]
	v_cndmask_b32_e64 v215, v216, v92, s[0:1]
	v_cndmask_b32_e64 v216, v218, v190, s[0:1]
	v_cndmask_b32_e64 v218, v219, v194, s[2:3]
	v_cndmask_b32_e64 v219, v221, v210, s[2:3]
	v_cndmask_b32_e64 v223, v217, v188, s[2:3]
	v_cndmask_b32_e64 v217, v220, v205, s[0:1]
	v_pk_fma_f32 v[218:219], v[118:119], v[218:219], v[126:127]
	v_cndmask_b32_e64 v214, v214, v152, s[0:1]
	v_pk_fma_f32 v[220:221], v[116:117], v[222:223], v[124:125]
	v_pk_fma_f32 v[216:217], v[114:115], v[216:217], v[218:219]
	v_pk_fma_f32 v[214:215], v[112:113], v[214:215], v[220:221]
	v_pk_fma_f32 v[138:139], v[122:123], v[138:139], v[216:217]
	v_cndmask_b32_e64 v216, v156, v94, s[2:3]
	v_cndmask_b32_e64 v217, v188, v189, s[2:3]
	v_cndmask_b32_e64 v220, v194, v192, s[2:3]
	v_cndmask_b32_e64 v221, v210, v195, s[2:3]
	v_pk_fma_f32 v[140:141], v[120:121], v[140:141], v[214:215]
	v_cndmask_b32_e64 v214, v152, v93, s[0:1]
	v_cndmask_b32_e64 v215, v92, v95, s[0:1]
	v_cndmask_b32_e64 v218, v190, v191, s[0:1]
	v_cndmask_b32_e64 v219, v205, v193, s[0:1]
	v_pk_fma_f32 v[220:221], v[118:119], v[220:221], v[126:127]
	v_pk_fma_f32 v[216:217], v[116:117], v[216:217], v[124:125]
	v_cndmask_b32_e64 v92, v191, v158, s[0:1]
	v_pk_fma_f32 v[214:215], v[112:113], v[214:215], v[216:217]
	v_pk_fma_f32 v[216:217], v[114:115], v[218:219], v[220:221]
	v_pk_fma_f32 v[214:215], v[120:121], v[84:85], v[214:215]
	v_pk_fma_f32 v[216:217], v[122:123], v[86:87], v[216:217]
	v_cndmask_b32_e64 v86, v94, v154, s[2:3]
	v_cndmask_b32_e64 v85, v95, v155, s[0:1]
	v_cndmask_b32_e64 v87, v189, v157, s[2:3]
	v_cndmask_b32_e64 v94, v192, v159, s[2:3]
	v_cndmask_b32_e64 v95, v195, v187, s[2:3]
	v_cndmask_b32_e64 v84, v93, v153, s[0:1]
	v_cndmask_b32_e64 v93, v193, v186, s[0:1]
	v_pk_fma_f32 v[94:95], v[118:119], v[94:95], v[126:127]
	v_pk_fma_f32 v[86:87], v[116:117], v[86:87], v[124:125]
	v_readlane_b32 s4, v249, 21
	v_pk_fma_f32 v[84:85], v[112:113], v[84:85], v[86:87]
	v_pk_fma_f32 v[86:87], v[114:115], v[92:93], v[94:95]
	v_pk_fma_f32 v[94:95], v[120:121], v[150:151], v[84:85]
	v_pk_fma_f32 v[92:93], v[122:123], v[142:143], v[86:87]
	v_cndmask_b32_e64 v86, v154, v204, s[2:3]
	v_cndmask_b32_e64 v87, v157, v208, s[2:3]
	v_cndmask_b32_e64 v150, v159, v211, s[2:3]
	v_cndmask_b32_e64 v151, v187, v213, s[2:3]
	v_cndmask_b32_e64 v84, v153, v203, s[0:1]
	v_cndmask_b32_e64 v85, v155, v207, s[0:1]
	v_cndmask_b32_e64 v142, v158, v209, s[0:1]
	v_cndmask_b32_e64 v143, v186, v212, s[0:1]
	v_pk_fma_f32 v[118:119], v[118:119], v[150:151], v[126:127]
	v_pk_fma_f32 v[86:87], v[116:117], v[86:87], v[124:125]
	v_readlane_b32 s5, v249, 22
	v_pk_fma_f32 v[86:87], v[112:113], v[84:85], v[86:87]
	v_pk_fma_f32 v[84:85], v[114:115], v[142:143], v[118:119]
	v_pk_fma_f32 v[86:87], v[120:121], v[88:89], v[86:87]
	v_pk_fma_f32 v[84:85], v[122:123], v[90:91], v[84:85]
	v_add_u32_e32 v90, 0x80, v202
	v_mov_b64_e32 v[88:89], s[4:5]
	v_mad_i64_i32 v[88:89], s[4:5], v90, s72, v[88:89]
	v_lshl_add_u64 v[112:113], v[174:175], 1, v[88:89]
	v_mov_b32_e32 v88, v130
	v_mov_b32_e32 v89, v130
	v_pk_mul_f32 v[66:67], v[66:67], v[88:89]
	v_mov_b32_e32 v88, v128
	v_mov_b32_e32 v89, v128
	v_pk_mul_f32 v[70:71], v[70:71], v[88:89]
	v_mov_b32_dpp v114, v80 row_ror:1 row_mask:0xf bank_mask:0xf
	v_mov_b32_dpp v88, v76 row_ror:1 row_mask:0xf bank_mask:0xf
	v_mov_b32_dpp v115, v80 row_ror:2 row_mask:0xf bank_mask:0xf
	v_mov_b32_dpp v89, v76 row_ror:2 row_mask:0xf bank_mask:0xf
	v_cndmask_b32_e64 v76, v88, v114, s[0:1]
	v_cndmask_b32_e64 v88, v89, v115, s[2:3]
	v_mov_b32_dpp v116, v81 row_ror:1 row_mask:0xf bank_mask:0xf
	v_mov_b32_dpp v89, v77 row_ror:1 row_mask:0xf bank_mask:0xf
	v_mov_b32_dpp v117, v81 row_ror:2 row_mask:0xf bank_mask:0xf
	v_mov_b32_dpp v90, v77 row_ror:2 row_mask:0xf bank_mask:0xf
	v_cndmask_b32_e64 v77, v89, v116, s[0:1]
	v_cndmask_b32_e64 v89, v90, v117, s[2:3]
	v_mov_b32_dpp v118, v82 row_ror:1 row_mask:0xf bank_mask:0xf
	v_mov_b32_dpp v90, v78 row_ror:1 row_mask:0xf bank_mask:0xf
	v_mov_b32_dpp v119, v82 row_ror:2 row_mask:0xf bank_mask:0xf
	v_mov_b32_dpp v91, v78 row_ror:2 row_mask:0xf bank_mask:0xf
	v_cndmask_b32_e64 v78, v90, v118, s[0:1]
	v_cndmask_b32_e64 v90, v91, v119, s[2:3]
	v_mov_b32_dpp v120, v83 row_ror:1 row_mask:0xf bank_mask:0xf
	v_mov_b32_dpp v91, v79 row_ror:1 row_mask:0xf bank_mask:0xf
	v_mov_b32_dpp v121, v83 row_ror:2 row_mask:0xf bank_mask:0xf
	v_mov_b32_dpp v122, v79 row_ror:2 row_mask:0xf bank_mask:0xf
	v_cndmask_b32_e64 v79, v91, v120, s[0:1]
	v_cndmask_b32_e64 v91, v122, v121, s[2:3]
	v_pk_fma_f32 v[90:91], v[106:107], v[90:91], v[110:111]
	v_pk_fma_f32 v[88:89], v[104:105], v[88:89], v[108:109]
	v_pk_fma_f32 v[78:79], v[102:103], v[78:79], v[90:91]
	v_pk_fma_f32 v[76:77], v[100:101], v[76:77], v[88:89]
	v_pk_fma_f32 v[78:79], v[98:99], v[82:83], v[78:79]
	v_mul_f32_e32 v82, 0xbfb8aa3b, v140
	v_mul_f32_e32 v83, 0xbfb8aa3b, v141
	v_exp_f32_e32 v82, v82
	v_exp_f32_e32 v83, v83
	v_pk_fma_f32 v[76:77], v[96:97], v[80:81], v[76:77]
	v_mov_b32_e32 v129, v128
	v_add_f32_e32 v80, 1.0, v82
	v_add_f32_e32 v81, 1.0, v83
	v_mul_f32_e32 v82, 0xbfb8aa3b, v138
	v_mul_f32_e32 v83, 0xbfb8aa3b, v139
	v_exp_f32_e32 v82, v82
	v_exp_f32_e32 v83, v83
	v_rcp_f32_e32 v80, v80
	v_rcp_f32_e32 v81, v81
	v_add_f32_e32 v82, 1.0, v82
	v_add_f32_e32 v83, 1.0, v83
	v_rcp_f32_e32 v82, v82
	v_rcp_f32_e32 v83, v83
	v_pk_mul_f32 v[80:81], v[140:141], v[80:81]
	v_pk_mul_f32 v[68:69], v[68:69], v[128:129]
	v_pk_mul_f32 v[76:77], v[80:81], v[76:77]
	v_pk_mul_f32 v[80:81], v[138:139], v[82:83]
	v_pk_mul_f32 v[78:79], v[80:81], v[78:79]
	v_mov_b32_dpp v91, v69 row_ror:2 row_mask:0xf bank_mask:0xf
; #define LAS __attribute__((address_space(3)))
; DI unsigned cvtpk(float lo, float hi) { f32x2_t v = {lo, hi}; bf16x2_t b = __builtin_convertvector(v, bf16x2_t); return __builtin_bit_cast(unsigned, b); }
; DI float silu_f(float x) { return x * frcp(1.f + fexp2(-x * LOG2E)); }
; template <int CTRL> DI float dpp_ror(float v) { return __builtin_bit_cast(float, __builtin_amdgcn_update_dpp(0, __builtin_bit_cast(int, v), CTRL, 0xf, 0xf, false)); }
;     template <int GV>
;     DI void conv_cols(const Acc& acc, const Unit& u, int ai, int n, int G, int f, int fr, const float (&rs)[4], bool samp, int sb, const f32x4 (&cw)[4], f32x4 (&cg)[4], bf16_t* actp) const {
;     ...
;         for (int m = 0; m < 4; ++m) {
;             f32x4 p1, p2;
; #pragma unroll
;             for (int j = 0; j < 4; ++j) {
;                 const float prev = (m == 0) ? Hh[j] : X[m - 1][j];
;                 const float a1 = dpp_ror<0x121>(X[m][j]), b1 = dpp_ror<0x121>(prev);
;                 const float a2 = dpp_ror<0x122>(X[m][j]), b2 = dpp_ror<0x122>(prev);
;                 p1[j] = (fr >= 1) ? a1 : b1; p2[j] = (fr >= 2) ? a2 : b2;
;             }
;             const f32x4 c = cw[3] + cw[0] * p2 + cw[1] * p1 + cw[2] * X[m];
;             if (GV == 0) cg[m] = c;
;             else { u32x2 wv; wv.x = cvtpk(silu_f(cg[m][0]) * c[0], silu_f(cg[m][1]) * c[1]); wv.y = cvtpk(silu_f(cg[m][2]) * c[2], silu_f(cg[m][3]) * c[3]);
;                 *(u32x2*)(actp + (size_t)(m * 16) * FFP) = wv; }
;     DI void operator()(const Acc& acc, const Unit& u, int wr, int wc, int fr, int fq) const {
;     ...
;             for (int t = 0; t < 4; ++t) { cwg[t] = *(const LAS f32x4*)(cwl + t * 128 + fl); cwv[t] = *(const LAS f32x4*)(cwl + (4 + t) * 128 + fl); }
	v_cvt_pk_bf16_f32 v76, v76, v77
	v_cvt_pk_bf16_f32 v77, v78, v79
	v_mov_b32_dpp v90, v69 row_ror:1 row_mask:0xf bank_mask:0xf
	v_cndmask_b32_e64 v79, v117, v91, s[2:3]
	global_store_dwordx2 v[112:113], v[76:77], off
	v_cndmask_b32_e64 v77, v116, v90, s[0:1]
	v_mov_b32_dpp v117, v70 row_ror:2 row_mask:0xf bank_mask:0xf
	v_mov_b32_dpp v116, v70 row_ror:1 row_mask:0xf bank_mask:0xf
	v_cndmask_b32_e64 v82, v119, v117, s[2:3]
	v_mov_b32_dpp v89, v68 row_ror:2 row_mask:0xf bank_mask:0xf
	v_cndmask_b32_e64 v80, v118, v116, s[0:1]
	v_mov_b32_dpp v119, v71 row_ror:2 row_mask:0xf bank_mask:0xf
	v_mov_b32_dpp v88, v68 row_ror:1 row_mask:0xf bank_mask:0xf
	v_cndmask_b32_e64 v78, v115, v89, s[2:3]
	v_mov_b32_dpp v118, v71 row_ror:1 row_mask:0xf bank_mask:0xf
	v_cndmask_b32_e64 v83, v121, v119, s[2:3]
	v_cndmask_b32_e64 v76, v114, v88, s[0:1]
	v_cndmask_b32_e64 v81, v120, v118, s[0:1]
	v_pk_fma_f32 v[82:83], v[106:107], v[82:83], v[110:111]
	v_pk_fma_f32 v[78:79], v[104:105], v[78:79], v[108:109]
	v_mov_b32_e32 v131, v130
	v_pk_fma_f32 v[76:77], v[100:101], v[76:77], v[78:79]
	v_pk_fma_f32 v[78:79], v[102:103], v[80:81], v[82:83]
	v_pk_fma_f32 v[68:69], v[96:97], v[68:69], v[76:77]
	v_pk_fma_f32 v[70:71], v[98:99], v[70:71], v[78:79]
	v_mul_f32_e32 v78, 0xbfb8aa3b, v214
	v_mul_f32_e32 v79, 0xbfb8aa3b, v215
	v_exp_f32_e32 v78, v78
	v_exp_f32_e32 v79, v79
	v_pk_mul_f32 v[64:65], v[64:65], v[130:131]
	v_add_f32_e32 v76, 1.0, v78
	v_add_f32_e32 v77, 1.0, v79
	v_mul_f32_e32 v78, 0xbfb8aa3b, v216
	v_mul_f32_e32 v79, 0xbfb8aa3b, v217
	v_exp_f32_e32 v78, v78
	v_exp_f32_e32 v79, v79
	v_rcp_f32_e32 v76, v76
	v_rcp_f32_e32 v77, v77
	v_add_f32_e32 v78, 1.0, v78
	v_add_f32_e32 v79, 1.0, v79
	v_rcp_f32_e32 v78, v78
	v_rcp_f32_e32 v79, v79
	v_pk_mul_f32 v[76:77], v[214:215], v[76:77]
	v_pk_mul_f32 v[68:69], v[76:77], v[68:69]
	v_pk_mul_f32 v[76:77], v[216:217], v[78:79]
	v_add_co_u32_e32 v114, vcc, s77, v112
	v_pk_mul_f32 v[70:71], v[76:77], v[70:71]
	v_mov_b32_dpp v81, v64 row_ror:2 row_mask:0xf bank_mask:0xf
	v_mov_b32_dpp v83, v65 row_ror:2 row_mask:0xf bank_mask:0xf
	v_cvt_pk_bf16_f32 v68, v68, v69
	v_cvt_pk_bf16_f32 v69, v70, v71
	v_addc_co_u32_e32 v115, vcc, 0, v113, vcc
	v_mov_b32_dpp v80, v64 row_ror:1 row_mask:0xf bank_mask:0xf
	v_cndmask_b32_e64 v70, v89, v81, s[2:3]
	v_mov_b32_dpp v82, v65 row_ror:1 row_mask:0xf bank_mask:0xf
	v_cndmask_b32_e64 v71, v91, v83, s[2:3]
	global_store_dwordx2 v[114:115], v[68:69], off offset:2048
	v_cndmask_b32_e64 v68, v88, v80, s[0:1]
	v_cndmask_b32_e64 v69, v90, v82, s[0:1]
	v_pk_fma_f32 v[70:71], v[104:105], v[70:71], v[108:109]
	v_pk_fma_f32 v[68:69], v[100:101], v[68:69], v[70:71]
	v_mul_f32_e32 v70, 0xbfb8aa3b, v94
	v_mul_f32_e32 v71, 0xbfb8aa3b, v95
	v_exp_f32_e32 v70, v70
	v_exp_f32_e32 v71, v71
	v_pk_fma_f32 v[64:65], v[96:97], v[64:65], v[68:69]
	v_add_f32_e32 v68, 1.0, v70
	v_add_f32_e32 v69, 1.0, v71
	v_mul_f32_e32 v70, 0xbfb8aa3b, v92
	v_mul_f32_e32 v71, 0xbfb8aa3b, v93
	v_exp_f32_e32 v70, v70
	v_exp_f32_e32 v71, v71
	v_rcp_f32_e32 v68, v68
	v_rcp_f32_e32 v69, v69
	v_add_f32_e32 v70, 1.0, v70
	v_add_f32_e32 v71, 1.0, v71
	v_mov_b32_dpp v89, v66 row_ror:2 row_mask:0xf bank_mask:0xf
	v_mov_b32_dpp v91, v67 row_ror:2 row_mask:0xf bank_mask:0xf
	v_rcp_f32_e32 v70, v70
	v_rcp_f32_e32 v71, v71
	v_mov_b32_dpp v88, v66 row_ror:1 row_mask:0xf bank_mask:0xf
	v_cndmask_b32_e64 v78, v117, v89, s[2:3]
	v_mov_b32_dpp v90, v67 row_ror:1 row_mask:0xf bank_mask:0xf
	v_cndmask_b32_e64 v79, v119, v91, s[2:3]
	v_cndmask_b32_e64 v76, v116, v88, s[0:1]
	v_cndmask_b32_e64 v77, v118, v90, s[0:1]
	v_pk_fma_f32 v[78:79], v[106:107], v[78:79], v[110:111]
	v_pk_mul_f32 v[68:69], v[94:95], v[68:69]
	v_pk_fma_f32 v[76:77], v[102:103], v[76:77], v[78:79]
	v_pk_mul_f32 v[64:65], v[68:69], v[64:65]
	v_pk_fma_f32 v[66:67], v[98:99], v[66:67], v[76:77]
	v_pk_mul_f32 v[68:69], v[92:93], v[70:71]
	v_add_co_u32_e32 v116, vcc, s82, v112
	v_pk_mul_f32 v[66:67], v[68:69], v[66:67]
	v_cvt_pk_bf16_f32 v64, v64, v65
	v_cvt_pk_bf16_f32 v65, v66, v67
	v_addc_co_u32_e32 v117, vcc, 0, v113, vcc
	global_store_dwordx2 v[116:117], v[64:65], off
	v_mov_b32_dpp v65, v72 row_ror:2 row_mask:0xf bank_mask:0xf
	v_mov_b32_dpp v69, v74 row_ror:2 row_mask:0xf bank_mask:0xf
	v_cndmask_b32_e64 v66, v81, v65, s[2:3]
	v_mov_b32_dpp v67, v73 row_ror:2 row_mask:0xf bank_mask:0xf
	v_cndmask_b32_e64 v70, v89, v69, s[2:3]
	v_mov_b32_dpp v71, v75 row_ror:2 row_mask:0xf bank_mask:0xf
	v_mov_b32_dpp v64, v72 row_ror:1 row_mask:0xf bank_mask:0xf
	v_mov_b32_dpp v65, v73 row_ror:1 row_mask:0xf bank_mask:0xf
	v_cndmask_b32_e64 v67, v83, v67, s[2:3]
	v_mov_b32_dpp v68, v74 row_ror:1 row_mask:0xf bank_mask:0xf
	v_mov_b32_dpp v69, v75 row_ror:1 row_mask:0xf bank_mask:0xf
	v_cndmask_b32_e64 v71, v91, v71, s[2:3]
	v_cndmask_b32_e64 v64, v80, v64, s[0:1]
	v_cndmask_b32_e64 v65, v82, v65, s[0:1]
	v_cndmask_b32_e64 v68, v88, v68, s[0:1]
	v_cndmask_b32_e64 v69, v90, v69, s[0:1]
	v_pk_fma_f32 v[70:71], v[106:107], v[70:71], v[110:111]
	v_pk_fma_f32 v[66:67], v[104:105], v[66:67], v[108:109]
	v_add_u32_e32 v76, 0x20a10, v201
	v_pk_fma_f32 v[64:65], v[100:101], v[64:65], v[66:67]
	v_pk_fma_f32 v[66:67], v[102:103], v[68:69], v[70:71]
	v_mul_f32_e32 v68, 0xbfb8aa3b, v86
	v_mul_f32_e32 v69, 0xbfb8aa3b, v87
	v_exp_f32_e32 v68, v68
	v_exp_f32_e32 v69, v69
	v_mul_f32_e32 v70, 0xbfb8aa3b, v84
	v_mul_f32_e32 v71, 0xbfb8aa3b, v85
	v_exp_f32_e32 v70, v70
	v_exp_f32_e32 v71, v71
	v_add_f32_e32 v68, 1.0, v68
	v_add_f32_e32 v69, 1.0, v69
	v_rcp_f32_e32 v68, v68
	v_rcp_f32_e32 v69, v69
	v_add_f32_e32 v70, 1.0, v70
	v_add_f32_e32 v71, 1.0, v71
	v_rcp_f32_e32 v70, v70
	v_rcp_f32_e32 v71, v71
	v_pk_fma_f32 v[64:65], v[96:97], v[72:73], v[64:65]
	v_pk_mul_f32 v[68:69], v[86:87], v[68:69]
	v_pk_fma_f32 v[66:67], v[98:99], v[74:75], v[66:67]
	v_pk_mul_f32 v[64:65], v[68:69], v[64:65]
	v_pk_mul_f32 v[68:69], v[84:85], v[70:71]
	v_cvt_pk_bf16_f32 v64, v64, v65
	v_pk_mul_f32 v[66:67], v[68:69], v[66:67]
	v_add_u32_e32 v77, 0x21210, v201
	v_cvt_pk_bf16_f32 v65, v66, v67
	v_add_co_u32_e32 v66, vcc, s83, v112
	v_mov_b32_e32 v96, v184
	s_nop 0
	v_addc_co_u32_e32 v67, vcc, 0, v113, vcc
	global_store_dwordx2 v[66:67], v[64:65], off offset:2048
	v_add_u32_e32 v64, 0x20410, v201
	v_add_u32_e32 v65, 0x20c10, v201
	ds_read_b128 v[84:87], v64
	ds_read_b128 v[72:75], v65
	v_add_u32_e32 v64, 0x20610, v201
	v_add_u32_e32 v65, 0x20e10, v201
	ds_read_b128 v[80:83], v64
	ds_read_b128 v[68:71], v65
	v_add_u32_e32 v64, 0x20810, v201
	v_add_u32_e32 v65, 0x21010, v201
	ds_read_b128 v[88:91], v64
	ds_read_b128 v[64:67], v65
	ds_read_b128 v[92:95], v76
	ds_read_b128 v[76:79], v77
	v_mov_b32_e32 v97, v184
	v_pk_mul_f32 v[100:101], v[60:61], v[184:185]
	v_mov_b32_e32 v60, v182
	v_mov_b32_e32 v61, v182
	v_pk_mul_f32 v[98:99], v[62:63], v[96:97]
	v_pk_mul_f32 v[58:59], v[58:59], v[60:61]
	v_pk_mul_f32 v[56:57], v[56:57], v[182:183]
	s_and_b64 vcc, exec, s[66:67]
	s_mov_b64 s[4:5], -1
	s_cbranch_vccnz .LBB0_882
;     template <int GV>
;     DI void conv_cols(const Acc& acc, const Unit& u, int ai, int n, int G, int f, int fr, const float (&rs)[4], bool samp, int sb, const f32x4 (&cw)[4], f32x4 (&cg)[4], bf16_t* actp) const {
;     ...
;             float* rw = RAW + ((((size_t)u.pm * 4 + G) * 4) * 2 + GV) * FF + f;
;             if (fr < 2 || fr >= 14) *(f32x4*)(rw + (size_t)(fr < 2 ? fr : fr - 12) * 2 * FF) = (fr < 2) ? X[0] : X[3];
	s_and_saveexec_b64 s[4:5], s[14:15]
	s_cbranch_execz .LBB0_881
	s_add_u32 s6, s80, s31
	s_addc_u32 s7, s81, s8
	v_lshl_add_u64 v[60:61], v[174:175], 2, s[6:7]
	v_lshl_add_u64 v[96:97], v[60:61], 0, v[176:177]
	v_cndmask_b32_e64 v63, v59, v99, s[16:17]
	v_cndmask_b32_e64 v62, v58, v98, s[16:17]
	v_cndmask_b32_e64 v61, v57, v101, s[16:17]
	v_cndmask_b32_e64 v60, v56, v100, s[16:17]
	global_store_dwordx4 v[96:97], v[60:63], off offset:16

;     template <int GV>
;     DI void conv_cols(const Acc& acc, const Unit& u, int ai, int n, int G, int f, int fr, const float (&rs)[4], bool samp, int sb, const f32x4 (&cw)[4], f32x4 (&cg)[4], bf16_t* actp) const {
;     ...
;         if (samp) { if (fr >= 14) Hh = *(const f32x4*)(sconv + ((size_t)sb * 2 + (fr - 14)) * FF2 + GV * FF + f); }
.LBB0_882:
	v_mov_b32_e32 v60, 0
	s_andn2_b64 vcc, exec, s[4:5]
	v_mov_b32_e32 v61, 0
	v_mov_b32_e32 v62, 0
	v_mov_b32_e32 v63, 0
	s_cbranch_vccnz .LBB0_886
	v_mov_b32_e32 v63, 0
	v_mov_b32_e32 v62, 0
	v_mov_b32_e32 v61, 0
	v_mov_b32_e32 v60, 0
	s_and_saveexec_b64 s[4:5], s[42:43]
	s_cbranch_execz .LBB0_885
	s_ashr_i32 s11, s10, 31
	v_readlane_b32 s60, v250, 14
	v_readlane_b32 s61, v250, 15
	v_lshl_add_u64 v[60:61], s[10:11], 1, v[168:169]
	v_readlane_b32 s49, v250, 3
	v_mov_b64_e32 v[62:63], s[60:61]
	v_mad_u64_u32 v[62:63], s[6:7], v60, s71, v[62:63]
	v_mad_i32_i24 v63, v61, s71, v63
	v_lshl_add_u64 v[60:61], v[174:175], 2, v[62:63]
	global_load_dwordx4 v[60:63], v[60:61], off offset:16
	s_waitcnt vmcnt(0)

; template <int CTRL> DI float dpp_ror(float v) { return __builtin_bit_cast(float, __builtin_amdgcn_update_dpp(0, __builtin_bit_cast(int, v), CTRL, 0xf, 0xf, false)); }
;     template <int GV>
;     DI void conv_cols(const Acc& acc, const Unit& u, int ai, int n, int G, int f, int fr, const float (&rs)[4], bool samp, int sb, const f32x4 (&cw)[4], f32x4 (&cg)[4], bf16_t* actp) const {
;     ...
;         for (int m = 0; m < 4; ++m) X[m] = acc[ai][GV][m][n] * rs[m];
;         f32x4 Hh = (f32x4){0.f, 0.f, 0.f, 0.f};
;         if (samp) { if (fr >= 14) Hh = *(const f32x4*)(sconv + ((size_t)sb * 2 + (fr - 14)) * FF2 + GV * FF + f); }
;         else {
;             float* rw = RAW + ((((size_t)u.pm * 4 + G) * 4) * 2 + GV) * FF + f;
;             if (fr < 2 || fr >= 14) *(f32x4*)(rw + (size_t)(fr < 2 ? fr : fr - 12) * 2 * FF) = (fr < 2) ? X[0] : X[3];
;         }
;         if (fr >= 14) {
;             if (samp) *(f32x4*)(out + O_CONV_S + ((size_t)sb * 2 + (fr - 14)) * FF2 + GV * FF + f) = X[3];
;             else if ((u.pm & 31) == 31 && G == 3) *(f32x4*)(out + O_CONV_P + ((size_t)(u.pm >> 5) * 2 + (fr - 14)) * FF2 + GV * FF + f) = X[3];
;         }
; #pragma unroll
;         for (int m = 0; m < 4; ++m) {
;             f32x4 p1, p2;
; #pragma unroll
;             for (int j = 0; j < 4; ++j) {
;                 const float prev = (m == 0) ? Hh[j] : X[m - 1][j];
;                 const float a1 = dpp_ror<0x121>(X[m][j]), b1 = dpp_ror<0x121>(prev);
;                 const float a2 = dpp_ror<0x122>(X[m][j]), b2 = dpp_ror<0x122>(prev);
;                 p1[j] = (fr >= 1) ? a1 : b1; p2[j] = (fr >= 2) ? a2 : b2;
.LBB0_891:
	s_or_b64 exec, exec, s[4:5]
	v_pk_mul_f32 v[104:105], v[48:49], v[180:181]
	v_mov_b32_e32 v48, v178
	v_mov_b32_e32 v49, v178
	v_mov_b32_e32 v102, v180
	v_mov_b32_e32 v103, v180
	v_pk_mul_f32 v[54:55], v[54:55], v[48:49]
	v_mov_b32_e32 v48, v184
	v_mov_b32_e32 v49, v184
	v_or_b32_e32 v96, 4, v174
	v_pk_mul_f32 v[102:103], v[50:51], v[102:103]
	v_pk_mul_f32 v[52:53], v[52:53], v[178:179]
	v_mov_b32_dpp v156, v60 row_ror:1 row_mask:0xf bank_mask:0xf
	v_mov_b32_dpp v157, v60 row_ror:2 row_mask:0xf bank_mask:0xf
	v_mov_b32_dpp v158, v61 row_ror:1 row_mask:0xf bank_mask:0xf
	v_mov_b32_dpp v159, v61 row_ror:2 row_mask:0xf bank_mask:0xf
	v_mov_b32_dpp v186, v62 row_ror:1 row_mask:0xf bank_mask:0xf
	v_mov_b32_dpp v187, v62 row_ror:2 row_mask:0xf bank_mask:0xf
	v_mov_b32_dpp v188, v63 row_ror:1 row_mask:0xf bank_mask:0xf
	v_mov_b32_dpp v189, v63 row_ror:2 row_mask:0xf bank_mask:0xf
	v_pk_mul_f32 v[50:51], v[46:47], v[48:49]
	v_pk_mul_f32 v[48:49], v[44:45], v[184:185]
	v_mov_b32_e32 v44, v182
	v_mov_b32_e32 v45, v182
	v_ashrrev_i32_e32 v97, 31, v96
	v_mov_b32_dpp v106, v100 row_ror:1 row_mask:0xf bank_mask:0xf
	v_mov_b32_dpp v110, v100 row_ror:2 row_mask:0xf bank_mask:0xf
	v_mov_b32_dpp v60, v101 row_ror:1 row_mask:0xf bank_mask:0xf
	v_mov_b32_dpp v122, v101 row_ror:2 row_mask:0xf bank_mask:0xf
	v_mov_b32_dpp v124, v98 row_ror:1 row_mask:0xf bank_mask:0xf
	v_mov_b32_dpp v138, v98 row_ror:2 row_mask:0xf bank_mask:0xf
	v_mov_b32_dpp v142, v99 row_ror:1 row_mask:0xf bank_mask:0xf
	v_mov_b32_dpp v152, v99 row_ror:2 row_mask:0xf bank_mask:0xf
	v_mov_b32_dpp v61, v52 row_ror:1 row_mask:0xf bank_mask:0xf
	v_mov_b32_dpp v62, v52 row_ror:2 row_mask:0xf bank_mask:0xf
	v_mov_b32_dpp v63, v53 row_ror:1 row_mask:0xf bank_mask:0xf
	v_mov_b32_dpp v123, v53 row_ror:2 row_mask:0xf bank_mask:0xf
	v_mov_b32_dpp v125, v54 row_ror:1 row_mask:0xf bank_mask:0xf
	v_mov_b32_dpp v126, v54 row_ror:2 row_mask:0xf bank_mask:0xf
	v_mov_b32_dpp v127, v55 row_ror:1 row_mask:0xf bank_mask:0xf
	v_mov_b32_dpp v139, v55 row_ror:2 row_mask:0xf bank_mask:0xf
	v_mov_b32_dpp v107, v104 row_ror:1 row_mask:0xf bank_mask:0xf
	v_mov_b32_dpp v108, v104 row_ror:2 row_mask:0xf bank_mask:0xf
	v_mov_b32_dpp v109, v105 row_ror:1 row_mask:0xf bank_mask:0xf
	v_mov_b32_dpp v111, v105 row_ror:2 row_mask:0xf bank_mask:0xf
	v_mov_b32_dpp v118, v102 row_ror:1 row_mask:0xf bank_mask:0xf
	v_mov_b32_dpp v119, v102 row_ror:2 row_mask:0xf bank_mask:0xf
	v_mov_b32_dpp v120, v103 row_ror:1 row_mask:0xf bank_mask:0xf
	v_mov_b32_dpp v121, v103 row_ror:2 row_mask:0xf bank_mask:0xf
	v_mov_b32_dpp v140, v56 row_ror:1 row_mask:0xf bank_mask:0xf
	v_mov_b32_dpp v141, v56 row_ror:2 row_mask:0xf bank_mask:0xf
	v_mov_b32_dpp v143, v57 row_ror:1 row_mask:0xf bank_mask:0xf
	v_mov_b32_dpp v150, v57 row_ror:2 row_mask:0xf bank_mask:0xf
	v_mov_b32_dpp v151, v58 row_ror:1 row_mask:0xf bank_mask:0xf
	v_mov_b32_dpp v153, v58 row_ror:2 row_mask:0xf bank_mask:0xf
	v_mov_b32_dpp v154, v59 row_ror:1 row_mask:0xf bank_mask:0xf
	v_mov_b32_dpp v155, v59 row_ror:2 row_mask:0xf bank_mask:0xf
	v_pk_mul_f32 v[42:43], v[42:43], v[44:45]
	v_pk_mul_f32 v[40:41], v[40:41], v[182:183]
	s_and_b64 vcc, exec, s[66:67]
	s_mov_b64 s[4:5], -1
	s_cbranch_vccnz .LBB0_895
	s_and_saveexec_b64 s[4:5], s[14:15]
	s_cbranch_execz .LBB0_894
	s_add_u32 s6, s80, s31
	s_addc_u32 s7, s81, s8
	v_lshl_add_u64 v[44:45], s[6:7], 0, v[176:177]
	v_lshl_add_u64 v[182:183], v[96:97], 2, v[44:45]
	v_add_co_u32_e32 v182, vcc, 0x5000, v182
	v_cndmask_b32_e64 v47, v43, v51, s[16:17]
	v_cndmask_b32_e64 v46, v42, v50, s[16:17]
	v_cndmask_b32_e64 v45, v41, v49, s[16:17]
	v_cndmask_b32_e64 v44, v40, v48, s[16:17]
	v_addc_co_u32_e32 v183, vcc, 0, v183, vcc
	global_store_dwordx4 v[182:183], v[44:47], off offset:2048

;     template <int GV>
;     DI void conv_cols(const Acc& acc, const Unit& u, int ai, int n, int G, int f, int fr, const float (&rs)[4], bool samp, int sb, const f32x4 (&cw)[4], f32x4 (&cg)[4], bf16_t* actp) const {
;     ...
;         if (samp) { if (fr >= 14) Hh = *(const f32x4*)(sconv + ((size_t)sb * 2 + (fr - 14)) * FF2 + GV * FF + f); }
.LBB0_895:
	v_mov_b32_e32 v44, 0
	s_andn2_b64 vcc, exec, s[4:5]
	v_mov_b32_e32 v45, 0
	v_mov_b32_e32 v46, 0
	v_mov_b32_e32 v47, 0
	s_cbranch_vccnz .LBB0_899
	v_mov_b32_e32 v47, 0
	v_mov_b32_e32 v46, 0
	v_mov_b32_e32 v45, 0
	v_mov_b32_e32 v44, 0
	s_and_saveexec_b64 s[4:5], s[42:43]
	s_cbranch_execz .LBB0_898
	s_ashr_i32 s11, s10, 31
	v_readlane_b32 s60, v250, 14
	v_readlane_b32 s61, v250, 15
	v_lshl_add_u64 v[44:45], s[10:11], 1, v[168:169]
	v_readlane_b32 s49, v250, 3
	v_mov_b64_e32 v[46:47], s[60:61]
	v_mad_u64_u32 v[46:47], s[6:7], v44, s71, v[46:47]
	v_mad_i32_i24 v47, v45, s71, v47
	v_lshl_add_u64 v[44:45], v[96:97], 2, v[46:47]
	v_add_co_u32_e32 v44, vcc, 0x5000, v44
	v_readlane_b32 s50, v250, 4
	s_nop 0
	v_addc_co_u32_e32 v45, vcc, 0, v45, vcc
	global_load_dwordx4 v[44:47], v[44:45], off offset:2048
	s_waitcnt vmcnt(0)

; DI unsigned cvtpk(float lo, float hi) { f32x2_t v = {lo, hi}; bf16x2_t b = __builtin_convertvector(v, bf16x2_t); return __builtin_bit_cast(unsigned, b); }
; DI float silu_f(float x) { return x * frcp(1.f + fexp2(-x * LOG2E)); }
; template <int CTRL> DI float dpp_ror(float v) { return __builtin_bit_cast(float, __builtin_amdgcn_update_dpp(0, __builtin_bit_cast(int, v), CTRL, 0xf, 0xf, false)); }
;     template <int GV>
;     DI void conv_cols(const Acc& acc, const Unit& u, int ai, int n, int G, int f, int fr, const float (&rs)[4], bool samp, int sb, const f32x4 (&cw)[4], f32x4 (&cg)[4], bf16_t* actp) const {
;     ...
;         for (int m = 0; m < 4; ++m) {
;             f32x4 p1, p2;
; #pragma unroll
;             for (int j = 0; j < 4; ++j) {
;                 const float prev = (m == 0) ? Hh[j] : X[m - 1][j];
;                 const float a1 = dpp_ror<0x121>(X[m][j]), b1 = dpp_ror<0x121>(prev);
;                 const float a2 = dpp_ror<0x122>(X[m][j]), b2 = dpp_ror<0x122>(prev);
;                 p1[j] = (fr >= 1) ? a1 : b1; p2[j] = (fr >= 2) ? a2 : b2;
;             }
;             const f32x4 c = cw[3] + cw[0] * p2 + cw[1] * p1 + cw[2] * X[m];
;             if (GV == 0) cg[m] = c;
;             else { u32x2 wv; wv.x = cvtpk(silu_f(cg[m][0]) * c[0], silu_f(cg[m][1]) * c[1]); wv.y = cvtpk(silu_f(cg[m][2]) * c[2], silu_f(cg[m][3]) * c[3]);
;                 *(u32x2*)(actp + (size_t)(m * 16) * FFP) = wv; }
.LBB0_904:
	s_or_b64 exec, exec, s[4:5]
	v_cndmask_b32_e64 v184, v187, v138, s[2:3]
	v_cndmask_b32_e64 v185, v189, v152, s[2:3]
	v_cndmask_b32_e64 v182, v157, v110, s[2:3]
	v_cndmask_b32_e64 v157, v158, v60, s[0:1]
	v_cndmask_b32_e64 v183, v159, v122, s[2:3]
	v_cndmask_b32_e64 v158, v186, v124, s[0:1]
	v_cndmask_b32_e64 v159, v188, v142, s[0:1]
	s_waitcnt lgkmcnt(1)
	v_pk_fma_f32 v[184:185], v[86:87], v[184:185], v[94:95]
	v_cndmask_b32_e64 v156, v156, v106, s[0:1]
	v_pk_fma_f32 v[182:183], v[84:85], v[182:183], v[92:93]
	v_pk_fma_f32 v[158:159], v[82:83], v[158:159], v[184:185]
	v_pk_fma_f32 v[156:157], v[80:81], v[156:157], v[182:183]
	v_pk_fma_f32 v[98:99], v[98:99], v[90:91], v[158:159]
	v_cndmask_b32_e64 v158, v110, v62, s[2:3]
	v_cndmask_b32_e64 v159, v122, v123, s[2:3]
	v_cndmask_b32_e64 v184, v138, v126, s[2:3]
	v_cndmask_b32_e64 v185, v152, v139, s[2:3]
	v_pk_fma_f32 v[100:101], v[100:101], v[88:89], v[156:157]
	v_cndmask_b32_e64 v156, v106, v61, s[0:1]
	v_cndmask_b32_e64 v157, v60, v63, s[0:1]
	v_cndmask_b32_e64 v182, v124, v125, s[0:1]
	v_cndmask_b32_e64 v183, v142, v127, s[0:1]
	v_pk_fma_f32 v[184:185], v[86:87], v[184:185], v[94:95]
	v_pk_fma_f32 v[158:159], v[84:85], v[158:159], v[92:93]
	v_cndmask_b32_e64 v60, v125, v118, s[0:1]
	v_pk_fma_f32 v[156:157], v[80:81], v[156:157], v[158:159]
	v_pk_fma_f32 v[158:159], v[82:83], v[182:183], v[184:185]
	v_pk_fma_f32 v[156:157], v[52:53], v[88:89], v[156:157]
	v_pk_fma_f32 v[158:159], v[54:55], v[90:91], v[158:159]
	v_cndmask_b32_e64 v54, v62, v108, s[2:3]
	v_cndmask_b32_e64 v53, v63, v109, s[0:1]
	v_cndmask_b32_e64 v55, v123, v111, s[2:3]
	v_cndmask_b32_e64 v62, v126, v119, s[2:3]
	v_cndmask_b32_e64 v63, v139, v121, s[2:3]
	v_cndmask_b32_e64 v52, v61, v107, s[0:1]
	v_cndmask_b32_e64 v61, v127, v120, s[0:1]
	v_pk_fma_f32 v[62:63], v[86:87], v[62:63], v[94:95]
	v_pk_fma_f32 v[54:55], v[84:85], v[54:55], v[92:93]
	v_pk_fma_f32 v[52:53], v[80:81], v[52:53], v[54:55]
	v_pk_fma_f32 v[54:55], v[82:83], v[60:61], v[62:63]
	v_pk_fma_f32 v[62:63], v[104:105], v[88:89], v[52:53]
	v_pk_fma_f32 v[60:61], v[102:103], v[90:91], v[54:55]
	v_cndmask_b32_e64 v54, v108, v141, s[2:3]
	v_cndmask_b32_e64 v55, v111, v150, s[2:3]
	v_cndmask_b32_e64 v52, v107, v140, s[0:1]
	v_cndmask_b32_e64 v53, v109, v143, s[0:1]
	v_pk_fma_f32 v[54:55], v[84:85], v[54:55], v[92:93]
	v_cndmask_b32_e64 v104, v119, v153, s[2:3]
	v_pk_fma_f32 v[54:55], v[80:81], v[52:53], v[54:55]
	v_cndmask_b32_e64 v105, v121, v155, s[2:3]
	v_pk_fma_f32 v[54:55], v[56:57], v[88:89], v[54:55]
	v_mov_b32_e32 v56, v180
	v_mov_b32_e32 v57, v180
	v_cndmask_b32_e64 v102, v118, v151, s[0:1]
	v_cndmask_b32_e64 v103, v120, v154, s[0:1]
	v_pk_fma_f32 v[104:105], v[86:87], v[104:105], v[94:95]
	v_pk_mul_f32 v[34:35], v[34:35], v[56:57]
	v_mov_b32_e32 v56, v178
	v_mov_b32_e32 v57, v178
	v_pk_fma_f32 v[52:53], v[82:83], v[102:103], v[104:105]
	v_pk_mul_f32 v[38:39], v[38:39], v[56:57]
	v_mov_b32_dpp v102, v48 row_ror:1 row_mask:0xf bank_mask:0xf
	v_mov_b32_dpp v56, v44 row_ror:1 row_mask:0xf bank_mask:0xf
	v_mov_b32_dpp v103, v48 row_ror:2 row_mask:0xf bank_mask:0xf
	v_mov_b32_dpp v57, v44 row_ror:2 row_mask:0xf bank_mask:0xf
	v_pk_fma_f32 v[52:53], v[58:59], v[90:91], v[52:53]
	v_cndmask_b32_e64 v44, v56, v102, s[0:1]
	v_cndmask_b32_e64 v56, v57, v103, s[2:3]
	v_mov_b32_dpp v104, v49 row_ror:1 row_mask:0xf bank_mask:0xf
	v_mov_b32_dpp v57, v45 row_ror:1 row_mask:0xf bank_mask:0xf
	v_mov_b32_dpp v105, v49 row_ror:2 row_mask:0xf bank_mask:0xf
	v_mov_b32_dpp v58, v45 row_ror:2 row_mask:0xf bank_mask:0xf
	v_cndmask_b32_e64 v45, v57, v104, s[0:1]
	v_cndmask_b32_e64 v57, v58, v105, s[2:3]
	v_mov_b32_dpp v106, v50 row_ror:1 row_mask:0xf bank_mask:0xf
	v_mov_b32_dpp v58, v46 row_ror:1 row_mask:0xf bank_mask:0xf
	v_mov_b32_dpp v107, v50 row_ror:2 row_mask:0xf bank_mask:0xf
	v_mov_b32_dpp v59, v46 row_ror:2 row_mask:0xf bank_mask:0xf
	v_cndmask_b32_e64 v46, v58, v106, s[0:1]
	v_cndmask_b32_e64 v58, v59, v107, s[2:3]
	v_mov_b32_dpp v108, v51 row_ror:1 row_mask:0xf bank_mask:0xf
	v_mov_b32_dpp v59, v47 row_ror:1 row_mask:0xf bank_mask:0xf
	v_mov_b32_dpp v109, v51 row_ror:2 row_mask:0xf bank_mask:0xf
	v_mov_b32_dpp v110, v47 row_ror:2 row_mask:0xf bank_mask:0xf
	v_cndmask_b32_e64 v47, v59, v108, s[0:1]
	v_cndmask_b32_e64 v59, v110, v109, s[2:3]
	s_waitcnt lgkmcnt(0)
; DI unsigned cvtpk(float lo, float hi) { f32x2_t v = {lo, hi}; bf16x2_t b = __builtin_convertvector(v, bf16x2_t); return __builtin_bit_cast(unsigned, b); }
; DI float silu_f(float x) { return x * frcp(1.f + fexp2(-x * LOG2E)); }
; template <int CTRL> DI float dpp_ror(float v) { return __builtin_bit_cast(float, __builtin_amdgcn_update_dpp(0, __builtin_bit_cast(int, v), CTRL, 0xf, 0xf, false)); }
;     template <int GV>
;     DI void conv_cols(const Acc& acc, const Unit& u, int ai, int n, int G, int f, int fr, const float (&rs)[4], bool samp, int sb, const f32x4 (&cw)[4], f32x4 (&cg)[4], bf16_t* actp) const {
;     ...
;         for (int m = 0; m < 4; ++m) {
;             f32x4 p1, p2;
; #pragma unroll
;             for (int j = 0; j < 4; ++j) {
;                 const float prev = (m == 0) ? Hh[j] : X[m - 1][j];
;                 const float a1 = dpp_ror<0x121>(X[m][j]), b1 = dpp_ror<0x121>(prev);
;                 const float a2 = dpp_ror<0x122>(X[m][j]), b2 = dpp_ror<0x122>(prev);
;                 p1[j] = (fr >= 1) ? a1 : b1; p2[j] = (fr >= 2) ? a2 : b2;
;             }
;             const f32x4 c = cw[3] + cw[0] * p2 + cw[1] * p1 + cw[2] * X[m];
;             if (GV == 0) cg[m] = c;
;             else { u32x2 wv; wv.x = cvtpk(silu_f(cg[m][0]) * c[0], silu_f(cg[m][1]) * c[1]); wv.y = cvtpk(silu_f(cg[m][2]) * c[2], silu_f(cg[m][3]) * c[3]);
;                 *(u32x2*)(actp + (size_t)(m * 16) * FFP) = wv; }
	v_pk_fma_f32 v[58:59], v[74:75], v[58:59], v[78:79]
	v_pk_fma_f32 v[56:57], v[72:73], v[56:57], v[76:77]
	v_pk_fma_f32 v[46:47], v[70:71], v[46:47], v[58:59]
	v_pk_fma_f32 v[44:45], v[68:69], v[44:45], v[56:57]
	v_pk_fma_f32 v[46:47], v[50:51], v[66:67], v[46:47]
	v_mul_f32_e32 v50, 0xbfb8aa3b, v100
	v_mul_f32_e32 v51, 0xbfb8aa3b, v101
	v_exp_f32_e32 v50, v50
	v_exp_f32_e32 v51, v51
	v_pk_fma_f32 v[44:45], v[48:49], v[64:65], v[44:45]
	v_pk_mul_f32 v[36:37], v[36:37], v[178:179]
	v_add_f32_e32 v48, 1.0, v50
	v_add_f32_e32 v49, 1.0, v51
	v_mul_f32_e32 v50, 0xbfb8aa3b, v98
	v_mul_f32_e32 v51, 0xbfb8aa3b, v99
	v_exp_f32_e32 v50, v50
	v_exp_f32_e32 v51, v51
	v_rcp_f32_e32 v48, v48
	v_rcp_f32_e32 v49, v49
	v_add_f32_e32 v50, 1.0, v50
	v_add_f32_e32 v51, 1.0, v51
	v_rcp_f32_e32 v50, v50
	v_rcp_f32_e32 v51, v51
	v_pk_mul_f32 v[48:49], v[100:101], v[48:49]
	v_pk_mul_f32 v[44:45], v[48:49], v[44:45]
	v_pk_mul_f32 v[48:49], v[98:99], v[50:51]
	v_pk_mul_f32 v[46:47], v[48:49], v[46:47]
	v_mov_b32_dpp v57, v36 row_ror:2 row_mask:0xf bank_mask:0xf
	v_mov_b32_dpp v59, v37 row_ror:2 row_mask:0xf bank_mask:0xf
	v_mov_b32_dpp v99, v38 row_ror:2 row_mask:0xf bank_mask:0xf
	v_mov_b32_dpp v101, v39 row_ror:2 row_mask:0xf bank_mask:0xf
	v_cvt_pk_bf16_f32 v44, v44, v45
	v_cvt_pk_bf16_f32 v45, v46, v47
	v_mov_b32_dpp v56, v36 row_ror:1 row_mask:0xf bank_mask:0xf
	v_cndmask_b32_e64 v46, v103, v57, s[2:3]
	v_mov_b32_dpp v58, v37 row_ror:1 row_mask:0xf bank_mask:0xf
	v_cndmask_b32_e64 v47, v105, v59, s[2:3]
	v_mov_b32_dpp v98, v38 row_ror:1 row_mask:0xf bank_mask:0xf
	v_cndmask_b32_e64 v50, v107, v99, s[2:3]
	v_mov_b32_dpp v100, v39 row_ror:1 row_mask:0xf bank_mask:0xf
	v_cndmask_b32_e64 v51, v109, v101, s[2:3]
	global_store_dwordx2 v[148:149], v[44:45], off offset:8
	v_cndmask_b32_e64 v44, v102, v56, s[0:1]
	v_cndmask_b32_e64 v45, v104, v58, s[0:1]
	v_cndmask_b32_e64 v48, v106, v98, s[0:1]
	v_cndmask_b32_e64 v49, v108, v100, s[0:1]
	v_pk_fma_f32 v[50:51], v[74:75], v[50:51], v[78:79]
	v_pk_fma_f32 v[46:47], v[72:73], v[46:47], v[76:77]
	v_pk_mul_f32 v[32:33], v[32:33], v[180:181]
	v_pk_fma_f32 v[44:45], v[68:69], v[44:45], v[46:47]
	v_pk_fma_f32 v[46:47], v[70:71], v[48:49], v[50:51]
	v_pk_fma_f32 v[36:37], v[36:37], v[64:65], v[44:45]
	v_pk_fma_f32 v[38:39], v[38:39], v[66:67], v[46:47]
	v_mul_f32_e32 v46, 0xbfb8aa3b, v156
	v_mul_f32_e32 v47, 0xbfb8aa3b, v157
	v_exp_f32_e32 v46, v46
	v_exp_f32_e32 v47, v47
	v_add_f32_e32 v44, 1.0, v46
	v_add_f32_e32 v45, 1.0, v47
	v_mul_f32_e32 v46, 0xbfb8aa3b, v158
	v_mul_f32_e32 v47, 0xbfb8aa3b, v159
	v_exp_f32_e32 v46, v46
	v_exp_f32_e32 v47, v47
	v_rcp_f32_e32 v44, v44
	v_rcp_f32_e32 v45, v45
	v_add_f32_e32 v46, 1.0, v46
	v_add_f32_e32 v47, 1.0, v47
	v_rcp_f32_e32 v46, v46
	v_rcp_f32_e32 v47, v47
	v_pk_mul_f32 v[44:45], v[156:157], v[44:45]
	v_pk_mul_f32 v[36:37], v[44:45], v[36:37]
	v_pk_mul_f32 v[44:45], v[158:159], v[46:47]
	v_mov_b32_dpp v49, v32 row_ror:2 row_mask:0xf bank_mask:0xf
	v_pk_mul_f32 v[38:39], v[44:45], v[38:39]
	v_mov_b32_dpp v51, v33 row_ror:2 row_mask:0xf bank_mask:0xf
	v_cvt_pk_bf16_f32 v36, v36, v37
	v_cvt_pk_bf16_f32 v37, v38, v39
	v_mov_b32_dpp v48, v32 row_ror:1 row_mask:0xf bank_mask:0xf
	v_cndmask_b32_e64 v38, v57, v49, s[2:3]
	v_mov_b32_dpp v50, v33 row_ror:1 row_mask:0xf bank_mask:0xf
	v_cndmask_b32_e64 v39, v59, v51, s[2:3]
	global_store_dwordx2 v[132:133], v[36:37], off offset:2056
	v_cndmask_b32_e64 v36, v56, v48, s[0:1]
	v_cndmask_b32_e64 v37, v58, v50, s[0:1]
	v_pk_fma_f32 v[38:39], v[72:73], v[38:39], v[76:77]
	v_pk_fma_f32 v[36:37], v[68:69], v[36:37], v[38:39]
	v_mul_f32_e32 v38, 0xbfb8aa3b, v62
	v_mul_f32_e32 v39, 0xbfb8aa3b, v63
	v_exp_f32_e32 v38, v38
	v_exp_f32_e32 v39, v39
	v_pk_fma_f32 v[32:33], v[32:33], v[64:65], v[36:37]
	v_add_f32_e32 v36, 1.0, v38
	v_add_f32_e32 v37, 1.0, v39
; DI unsigned cvtpk(float lo, float hi) { f32x2_t v = {lo, hi}; bf16x2_t b = __builtin_convertvector(v, bf16x2_t); return __builtin_bit_cast(unsigned, b); }
; DI float silu_f(float x) { return x * frcp(1.f + fexp2(-x * LOG2E)); }
; template <int CTRL> DI float dpp_ror(float v) { return __builtin_bit_cast(float, __builtin_amdgcn_update_dpp(0, __builtin_bit_cast(int, v), CTRL, 0xf, 0xf, false)); }
;     template <int GV>
;     DI void conv_cols(const Acc& acc, const Unit& u, int ai, int n, int G, int f, int fr, const float (&rs)[4], bool samp, int sb, const f32x4 (&cw)[4], f32x4 (&cg)[4], bf16_t* actp) const {
;     ...
;             if (fr < 2 || fr >= 14) *(f32x4*)(rw + (size_t)(fr < 2 ? fr : fr - 12) * 2 * FF) = (fr < 2) ? X[0] : X[3];
;         }
;         if (fr >= 14) {
;             if (samp) *(f32x4*)(out + O_CONV_S + ((size_t)sb * 2 + (fr - 14)) * FF2 + GV * FF + f) = X[3];
;             else if ((u.pm & 31) == 31 && G == 3) *(f32x4*)(out + O_CONV_P + ((size_t)(u.pm >> 5) * 2 + (fr - 14)) * FF2 + GV * FF + f) = X[3];
;         }
; #pragma unroll
;         for (int m = 0; m < 4; ++m) {
;             f32x4 p1, p2;
; #pragma unroll
;             for (int j = 0; j < 4; ++j) {
;                 const float prev = (m == 0) ? Hh[j] : X[m - 1][j];
;                 const float a1 = dpp_ror<0x121>(X[m][j]), b1 = dpp_ror<0x121>(prev);
;                 const float a2 = dpp_ror<0x122>(X[m][j]), b2 = dpp_ror<0x122>(prev);
;                 p1[j] = (fr >= 1) ? a1 : b1; p2[j] = (fr >= 2) ? a2 : b2;
;             }
;             const f32x4 c = cw[3] + cw[0] * p2 + cw[1] * p1 + cw[2] * X[m];
;             if (GV == 0) cg[m] = c;
;             else { u32x2 wv; wv.x = cvtpk(silu_f(cg[m][0]) * c[0], silu_f(cg[m][1]) * c[1]); wv.y = cvtpk(silu_f(cg[m][2]) * c[2], silu_f(cg[m][3]) * c[3]);
;                 *(u32x2*)(actp + (size_t)(m * 16) * FFP) = wv; }
	v_mul_f32_e32 v38, 0xbfb8aa3b, v60
	v_mul_f32_e32 v39, 0xbfb8aa3b, v61
	v_exp_f32_e32 v38, v38
	v_exp_f32_e32 v39, v39
	v_rcp_f32_e32 v36, v36
	v_rcp_f32_e32 v37, v37
	v_add_f32_e32 v38, 1.0, v38
	v_add_f32_e32 v39, 1.0, v39
	v_mov_b32_dpp v57, v34 row_ror:2 row_mask:0xf bank_mask:0xf
	v_mov_b32_dpp v59, v35 row_ror:2 row_mask:0xf bank_mask:0xf
	v_rcp_f32_e32 v38, v38
	v_rcp_f32_e32 v39, v39
	v_mov_b32_dpp v56, v34 row_ror:1 row_mask:0xf bank_mask:0xf
	v_cndmask_b32_e64 v46, v99, v57, s[2:3]
	v_mov_b32_dpp v58, v35 row_ror:1 row_mask:0xf bank_mask:0xf
	v_cndmask_b32_e64 v47, v101, v59, s[2:3]
	v_cndmask_b32_e64 v44, v98, v56, s[0:1]
	v_cndmask_b32_e64 v45, v100, v58, s[0:1]
	v_pk_fma_f32 v[46:47], v[74:75], v[46:47], v[78:79]
	v_pk_mul_f32 v[36:37], v[62:63], v[36:37]
	v_pk_fma_f32 v[44:45], v[70:71], v[44:45], v[46:47]
	v_pk_mul_f32 v[32:33], v[36:37], v[32:33]
	v_pk_fma_f32 v[34:35], v[34:35], v[66:67], v[44:45]
	v_pk_mul_f32 v[36:37], v[60:61], v[38:39]
	v_cvt_pk_bf16_f32 v32, v32, v33
	v_pk_mul_f32 v[34:35], v[36:37], v[34:35]
	v_cvt_pk_bf16_f32 v33, v34, v35
	global_store_dwordx2 v[134:135], v[32:33], off offset:8
	v_mov_b32_dpp v37, v42 row_ror:2 row_mask:0xf bank_mask:0xf
	v_mov_b32_dpp v33, v40 row_ror:2 row_mask:0xf bank_mask:0xf
	v_cndmask_b32_e64 v34, v49, v33, s[2:3]
	v_mov_b32_dpp v35, v41 row_ror:2 row_mask:0xf bank_mask:0xf
	v_cndmask_b32_e64 v38, v57, v37, s[2:3]
	v_mov_b32_dpp v39, v43 row_ror:2 row_mask:0xf bank_mask:0xf
	v_mov_b32_dpp v32, v40 row_ror:1 row_mask:0xf bank_mask:0xf
	v_mov_b32_dpp v33, v41 row_ror:1 row_mask:0xf bank_mask:0xf
	v_cndmask_b32_e64 v35, v51, v35, s[2:3]
	v_mov_b32_dpp v36, v42 row_ror:1 row_mask:0xf bank_mask:0xf
	v_mov_b32_dpp v37, v43 row_ror:1 row_mask:0xf bank_mask:0xf
	v_cndmask_b32_e64 v39, v59, v39, s[2:3]
	v_cndmask_b32_e64 v32, v48, v32, s[0:1]
	v_cndmask_b32_e64 v33, v50, v33, s[0:1]
	v_cndmask_b32_e64 v36, v56, v36, s[0:1]
	v_cndmask_b32_e64 v37, v58, v37, s[0:1]
	v_pk_fma_f32 v[38:39], v[74:75], v[38:39], v[78:79]
	v_pk_fma_f32 v[34:35], v[72:73], v[34:35], v[76:77]
	v_pk_mul_f32 v[24:25], v[24:25], v[144:145]
	v_pk_fma_f32 v[32:33], v[68:69], v[32:33], v[34:35]
	v_pk_fma_f32 v[34:35], v[70:71], v[36:37], v[38:39]
	v_mul_f32_e32 v36, 0xbfb8aa3b, v54
	v_mul_f32_e32 v37, 0xbfb8aa3b, v55
	v_exp_f32_e32 v36, v36
	v_exp_f32_e32 v37, v37
	v_mul_f32_e32 v38, 0xbfb8aa3b, v52
	v_mul_f32_e32 v39, 0xbfb8aa3b, v53
	v_exp_f32_e32 v38, v38
	v_exp_f32_e32 v39, v39
	v_add_f32_e32 v36, 1.0, v36
	v_add_f32_e32 v37, 1.0, v37
	v_rcp_f32_e32 v36, v36
	v_rcp_f32_e32 v37, v37
	v_add_f32_e32 v38, 1.0, v38
	v_add_f32_e32 v39, 1.0, v39
	v_rcp_f32_e32 v38, v38
	v_rcp_f32_e32 v39, v39
	v_pk_fma_f32 v[32:33], v[40:41], v[64:65], v[32:33]
	v_pk_mul_f32 v[36:37], v[54:55], v[36:37]
	v_pk_fma_f32 v[34:35], v[42:43], v[66:67], v[34:35]
	v_pk_mul_f32 v[32:33], v[36:37], v[32:33]
	v_pk_mul_f32 v[36:37], v[52:53], v[38:39]
	v_cvt_pk_bf16_f32 v32, v32, v33
	v_pk_mul_f32 v[34:35], v[36:37], v[34:35]
	s_and_b64 vcc, exec, s[66:67]
	v_cvt_pk_bf16_f32 v33, v34, v35
	global_store_dwordx2 v[136:137], v[32:33], off offset:2056
	v_mov_b32_e32 v32, v146
	v_mov_b32_e32 v33, v146
	v_pk_mul_f32 v[34:35], v[28:29], v[146:147]
	v_mov_b32_e32 v28, v144
	v_mov_b32_e32 v29, v144
	v_pk_mul_f32 v[32:33], v[30:31], v[32:33]
	v_pk_mul_f32 v[26:27], v[26:27], v[28:29]
	s_mov_b64 s[4:5], -1
	s_cbranch_vccnz .LBB0_908
	s_and_saveexec_b64 s[4:5], s[14:15]
	s_cbranch_execz .LBB0_907
	s_add_u32 s6, s93, s31
	s_addc_u32 s7, s25, s8
	v_lshl_add_u64 v[28:29], v[174:175], 2, s[6:7]
	v_lshl_add_u64 v[36:37], v[28:29], 0, v[176:177]
	v_cndmask_b32_e64 v31, v27, v33, s[16:17]
	v_cndmask_b32_e64 v30, v26, v32, s[16:17]
	v_cndmask_b32_e64 v29, v25, v35, s[16:17]
	v_cndmask_b32_e64 v28, v24, v34, s[16:17]
	global_store_dwordx4 v[36:37], v[28:31], off offset:16

;     template <int GV>
;     DI void conv_cols(const Acc& acc, const Unit& u, int ai, int n, int G, int f, int fr, const float (&rs)[4], bool samp, int sb, const f32x4 (&cw)[4], f32x4 (&cg)[4], bf16_t* actp) const {
;     ...
;         if (samp) { if (fr >= 14) Hh = *(const f32x4*)(sconv + ((size_t)sb * 2 + (fr - 14)) * FF2 + GV * FF + f); }
.LBB0_908:
	v_mov_b32_e32 v28, 0
	s_andn2_b64 vcc, exec, s[4:5]
	v_mov_b32_e32 v29, 0
	v_mov_b32_e32 v30, 0
	v_mov_b32_e32 v31, 0
	s_cbranch_vccnz .LBB0_912
	v_mov_b32_e32 v31, 0
	v_mov_b32_e32 v30, 0
	v_mov_b32_e32 v29, 0
	v_mov_b32_e32 v28, 0
	s_and_saveexec_b64 s[4:5], s[42:43]
	s_cbranch_execz .LBB0_911
	s_ashr_i32 s21, s20, 31
	v_readlane_b32 s60, v250, 14
	v_readlane_b32 s61, v250, 15
	v_lshl_add_u64 v[28:29], s[20:21], 1, v[168:169]
	v_readlane_b32 s49, v250, 3
	v_mov_b64_e32 v[30:31], s[60:61]
	v_mad_u64_u32 v[30:31], s[6:7], v28, s71, v[30:31]
	v_mad_i32_i24 v31, v29, s71, v31
	v_lshl_add_u64 v[28:29], v[174:175], 2, v[30:31]
	global_load_dwordx4 v[28:31], v[28:29], off offset:16
	s_waitcnt vmcnt(0)

; template <int CTRL> DI float dpp_ror(float v) { return __builtin_bit_cast(float, __builtin_amdgcn_update_dpp(0, __builtin_bit_cast(int, v), CTRL, 0xf, 0xf, false)); }
;     template <int GV>
;     DI void conv_cols(const Acc& acc, const Unit& u, int ai, int n, int G, int f, int fr, const float (&rs)[4], bool samp, int sb, const f32x4 (&cw)[4], f32x4 (&cg)[4], bf16_t* actp) const {
;     ...
;         for (int m = 0; m < 4; ++m) X[m] = acc[ai][GV][m][n] * rs[m];
;         f32x4 Hh = (f32x4){0.f, 0.f, 0.f, 0.f};
;         if (samp) { if (fr >= 14) Hh = *(const f32x4*)(sconv + ((size_t)sb * 2 + (fr - 14)) * FF2 + GV * FF + f); }
;         else {
;             float* rw = RAW + ((((size_t)u.pm * 4 + G) * 4) * 2 + GV) * FF + f;
;             if (fr < 2 || fr >= 14) *(f32x4*)(rw + (size_t)(fr < 2 ? fr : fr - 12) * 2 * FF) = (fr < 2) ? X[0] : X[3];
;         }
;         if (fr >= 14) {
;             if (samp) *(f32x4*)(out + O_CONV_S + ((size_t)sb * 2 + (fr - 14)) * FF2 + GV * FF + f) = X[3];
;             else if ((u.pm & 31) == 31 && G == 3) *(f32x4*)(out + O_CONV_P + ((size_t)(u.pm >> 5) * 2 + (fr - 14)) * FF2 + GV * FF + f) = X[3];
;         }
; #pragma unroll
;         for (int m = 0; m < 4; ++m) {
;             f32x4 p1, p2;
; #pragma unroll
;             for (int j = 0; j < 4; ++j) {
;                 const float prev = (m == 0) ? Hh[j] : X[m - 1][j];
;                 const float a1 = dpp_ror<0x121>(X[m][j]), b1 = dpp_ror<0x121>(prev);
;                 const float a2 = dpp_ror<0x122>(X[m][j]), b2 = dpp_ror<0x122>(prev);
;                 p1[j] = (fr >= 1) ? a1 : b1; p2[j] = (fr >= 2) ? a2 : b2;
.LBB0_917:
	s_or_b64 exec, exec, s[4:5]
	v_mov_b32_e32 v36, v130
	v_mov_b32_e32 v37, v130
	v_pk_mul_f32 v[42:43], v[16:17], v[130:131]
	v_mov_b32_e32 v16, v128
	v_mov_b32_e32 v17, v128
	v_pk_mul_f32 v[38:39], v[20:21], v[128:129]
	v_mov_b32_e32 v20, v146
	v_mov_b32_e32 v21, v146
	v_pk_mul_f32 v[40:41], v[18:19], v[36:37]
	v_pk_mul_f32 v[36:37], v[22:23], v[16:17]
	v_mov_b32_dpp v46, v28 row_ror:1 row_mask:0xf bank_mask:0xf
	v_mov_b32_dpp v47, v28 row_ror:2 row_mask:0xf bank_mask:0xf
	v_mov_b32_dpp v49, v29 row_ror:1 row_mask:0xf bank_mask:0xf
	v_mov_b32_dpp v50, v29 row_ror:2 row_mask:0xf bank_mask:0xf
	v_mov_b32_dpp v52, v30 row_ror:1 row_mask:0xf bank_mask:0xf
	v_mov_b32_dpp v53, v30 row_ror:2 row_mask:0xf bank_mask:0xf
	v_mov_b32_dpp v55, v31 row_ror:1 row_mask:0xf bank_mask:0xf
	v_mov_b32_dpp v56, v31 row_ror:2 row_mask:0xf bank_mask:0xf
	v_pk_mul_f32 v[22:23], v[14:15], v[20:21]
	v_pk_mul_f32 v[20:21], v[12:13], v[146:147]
	v_mov_b32_e32 v12, v144
	v_mov_b32_e32 v13, v144
	v_mov_b32_dpp v44, v34 row_ror:1 row_mask:0xf bank_mask:0xf
	v_mov_b32_dpp v45, v34 row_ror:2 row_mask:0xf bank_mask:0xf
	v_mov_b32_dpp v28, v35 row_ror:1 row_mask:0xf bank_mask:0xf
	v_mov_b32_dpp v48, v35 row_ror:2 row_mask:0xf bank_mask:0xf
	v_mov_b32_dpp v29, v32 row_ror:1 row_mask:0xf bank_mask:0xf
	v_mov_b32_dpp v51, v32 row_ror:2 row_mask:0xf bank_mask:0xf
	v_mov_b32_dpp v30, v33 row_ror:1 row_mask:0xf bank_mask:0xf
	v_mov_b32_dpp v54, v33 row_ror:2 row_mask:0xf bank_mask:0xf
	v_mov_b32_dpp v57, v38 row_ror:1 row_mask:0xf bank_mask:0xf
	v_mov_b32_dpp v31, v38 row_ror:2 row_mask:0xf bank_mask:0xf
	v_mov_b32_dpp v59, v39 row_ror:1 row_mask:0xf bank_mask:0xf
	v_mov_b32_dpp v58, v39 row_ror:2 row_mask:0xf bank_mask:0xf
	v_mov_b32_dpp v61, v36 row_ror:1 row_mask:0xf bank_mask:0xf
	v_mov_b32_dpp v60, v36 row_ror:2 row_mask:0xf bank_mask:0xf
	v_mov_b32_dpp v63, v37 row_ror:1 row_mask:0xf bank_mask:0xf
	v_mov_b32_dpp v62, v37 row_ror:2 row_mask:0xf bank_mask:0xf
	v_mov_b32_dpp v99, v42 row_ror:1 row_mask:0xf bank_mask:0xf
	v_mov_b32_dpp v98, v42 row_ror:2 row_mask:0xf bank_mask:0xf
	v_mov_b32_dpp v101, v43 row_ror:1 row_mask:0xf bank_mask:0xf
	v_mov_b32_dpp v100, v43 row_ror:2 row_mask:0xf bank_mask:0xf
	v_mov_b32_dpp v103, v40 row_ror:1 row_mask:0xf bank_mask:0xf
	v_mov_b32_dpp v102, v40 row_ror:2 row_mask:0xf bank_mask:0xf
	v_mov_b32_dpp v105, v41 row_ror:1 row_mask:0xf bank_mask:0xf
	v_mov_b32_dpp v104, v41 row_ror:2 row_mask:0xf bank_mask:0xf
	v_mov_b32_dpp v17, v24 row_ror:1 row_mask:0xf bank_mask:0xf
	v_mov_b32_dpp v16, v24 row_ror:2 row_mask:0xf bank_mask:0xf
	v_mov_b32_dpp v19, v25 row_ror:1 row_mask:0xf bank_mask:0xf
	v_mov_b32_dpp v18, v25 row_ror:2 row_mask:0xf bank_mask:0xf
	v_mov_b32_dpp v107, v26 row_ror:1 row_mask:0xf bank_mask:0xf
	v_mov_b32_dpp v106, v26 row_ror:2 row_mask:0xf bank_mask:0xf
	v_mov_b32_dpp v109, v27 row_ror:1 row_mask:0xf bank_mask:0xf
	v_mov_b32_dpp v108, v27 row_ror:2 row_mask:0xf bank_mask:0xf
	v_pk_mul_f32 v[10:11], v[10:11], v[12:13]
	v_pk_mul_f32 v[8:9], v[8:9], v[144:145]
	s_and_b64 vcc, exec, s[66:67]
	s_mov_b64 s[4:5], -1
	s_cbranch_vccnz .LBB0_921
	s_and_saveexec_b64 s[4:5], s[14:15]
	s_cbranch_execz .LBB0_920
	s_add_u32 s6, s93, s31
	s_addc_u32 s7, s25, s8
	v_lshl_add_u64 v[12:13], s[6:7], 0, v[176:177]
	v_lshl_add_u64 v[110:111], v[96:97], 2, v[12:13]
	v_add_co_u32_e32 v110, vcc, 0x5000, v110
	v_cndmask_b32_e64 v15, v11, v23, s[16:17]
	v_cndmask_b32_e64 v14, v10, v22, s[16:17]
	v_cndmask_b32_e64 v13, v9, v21, s[16:17]
	v_cndmask_b32_e64 v12, v8, v20, s[16:17]
	v_addc_co_u32_e32 v111, vcc, 0, v111, vcc
	global_store_dwordx4 v[110:111], v[12:15], off offset:2048

;     template <int GV>
;     DI void conv_cols(const Acc& acc, const Unit& u, int ai, int n, int G, int f, int fr, const float (&rs)[4], bool samp, int sb, const f32x4 (&cw)[4], f32x4 (&cg)[4], bf16_t* actp) const {
;     ...
;         if (samp) { if (fr >= 14) Hh = *(const f32x4*)(sconv + ((size_t)sb * 2 + (fr - 14)) * FF2 + GV * FF + f); }
.LBB0_921:
	v_mov_b32_e32 v12, 0
	s_andn2_b64 vcc, exec, s[4:5]
	v_mov_b32_e32 v13, 0
	v_mov_b32_e32 v14, 0
	v_mov_b32_e32 v15, 0
	s_cbranch_vccnz .LBB0_925
	v_mov_b32_e32 v15, 0
	v_mov_b32_e32 v14, 0
	v_mov_b32_e32 v13, 0
	v_mov_b32_e32 v12, 0
	s_and_saveexec_b64 s[4:5], s[42:43]
	s_cbranch_execz .LBB0_924
	s_ashr_i32 s21, s20, 31
	v_readlane_b32 s60, v250, 14
	v_readlane_b32 s61, v250, 15
	v_lshl_add_u64 v[12:13], s[20:21], 1, v[168:169]
	v_readlane_b32 s49, v250, 3
	v_mov_b64_e32 v[14:15], s[60:61]
	v_mad_u64_u32 v[14:15], s[6:7], v12, s71, v[14:15]
	v_mad_i32_i24 v15, v13, s71, v15
	v_lshl_add_u64 v[12:13], v[96:97], 2, v[14:15]
	v_add_co_u32_e32 v12, vcc, 0x5000, v12
	v_readlane_b32 s50, v250, 4
	s_nop 0
	v_addc_co_u32_e32 v13, vcc, 0, v13, vcc
	global_load_dwordx4 v[12:15], v[12:13], off offset:2048
	s_waitcnt vmcnt(0)

; DI unsigned cvtpk(float lo, float hi) { f32x2_t v = {lo, hi}; bf16x2_t b = __builtin_convertvector(v, bf16x2_t); return __builtin_bit_cast(unsigned, b); }
; DI float silu_f(float x) { return x * frcp(1.f + fexp2(-x * LOG2E)); }
; template <int CTRL> DI float dpp_ror(float v) { return __builtin_bit_cast(float, __builtin_amdgcn_update_dpp(0, __builtin_bit_cast(int, v), CTRL, 0xf, 0xf, false)); }
;     template <int GV>
;     DI void conv_cols(const Acc& acc, const Unit& u, int ai, int n, int G, int f, int fr, const float (&rs)[4], bool samp, int sb, const f32x4 (&cw)[4], f32x4 (&cg)[4], bf16_t* actp) const {
;     ...
;         for (int m = 0; m < 4; ++m) {
;             f32x4 p1, p2;
; #pragma unroll
;             for (int j = 0; j < 4; ++j) {
;                 const float prev = (m == 0) ? Hh[j] : X[m - 1][j];
;                 const float a1 = dpp_ror<0x121>(X[m][j]), b1 = dpp_ror<0x121>(prev);
;                 const float a2 = dpp_ror<0x122>(X[m][j]), b2 = dpp_ror<0x122>(prev);
;                 p1[j] = (fr >= 1) ? a1 : b1; p2[j] = (fr >= 2) ? a2 : b2;
;             }
;             const f32x4 c = cw[3] + cw[0] * p2 + cw[1] * p1 + cw[2] * X[m];
;             if (GV == 0) cg[m] = c;
;             else { u32x2 wv; wv.x = cvtpk(silu_f(cg[m][0]) * c[0], silu_f(cg[m][1]) * c[1]); wv.y = cvtpk(silu_f(cg[m][2]) * c[2], silu_f(cg[m][3]) * c[3]);
;                 *(u32x2*)(actp + (size_t)(m * 16) * FFP) = wv; }
.LBB0_930:
	s_or_b64 exec, exec, s[4:5]
	v_cndmask_b32_e64 v96, v99, v17, s[0:1]
	v_cndmask_b32_e64 v16, v98, v16, s[2:3]
	v_cndmask_b32_e64 v17, v100, v18, s[2:3]
	v_cndmask_b32_e64 v97, v101, v19, s[0:1]
	v_cndmask_b32_e64 v18, v102, v106, s[2:3]
	v_cndmask_b32_e64 v19, v104, v108, s[2:3]
	v_pk_fma_f32 v[16:17], v[84:85], v[16:17], v[92:93]
	v_cndmask_b32_e64 v110, v103, v107, s[0:1]
	v_cndmask_b32_e64 v111, v105, v109, s[0:1]
	v_pk_fma_f32 v[18:19], v[86:87], v[18:19], v[94:95]
	v_pk_fma_f32 v[96:97], v[80:81], v[96:97], v[16:17]
	v_pk_fma_f32 v[16:17], v[82:83], v[110:111], v[18:19]
	v_pk_fma_f32 v[18:19], v[24:25], v[88:89], v[96:97]
	v_cndmask_b32_e64 v24, v57, v99, s[0:1]
	v_cndmask_b32_e64 v96, v31, v98, s[2:3]
	v_cndmask_b32_e64 v97, v58, v100, s[2:3]
	v_cndmask_b32_e64 v98, v60, v102, s[2:3]
	v_cndmask_b32_e64 v99, v62, v104, s[2:3]
	v_pk_fma_f32 v[16:17], v[26:27], v[90:91], v[16:17]
	v_cndmask_b32_e64 v25, v59, v101, s[0:1]
	v_cndmask_b32_e64 v26, v61, v103, s[0:1]
	v_cndmask_b32_e64 v27, v63, v105, s[0:1]
	v_pk_fma_f32 v[98:99], v[86:87], v[98:99], v[94:95]
	v_pk_fma_f32 v[96:97], v[84:85], v[96:97], v[92:93]
	v_pk_mul_f32 v[4:5], v[4:5], v[128:129]
	v_pk_fma_f32 v[96:97], v[80:81], v[24:25], v[96:97]
	v_pk_fma_f32 v[24:25], v[82:83], v[26:27], v[98:99]
	v_pk_fma_f32 v[26:27], v[42:43], v[88:89], v[96:97]
	v_pk_fma_f32 v[24:25], v[40:41], v[90:91], v[24:25]
	v_cndmask_b32_e64 v41, v28, v59, s[0:1]
	v_cndmask_b32_e64 v97, v48, v58, s[2:3]
	v_cndmask_b32_e64 v58, v51, v60, s[2:3]
	v_cndmask_b32_e64 v59, v54, v62, s[2:3]
	v_cndmask_b32_e64 v42, v29, v61, s[0:1]
	v_cndmask_b32_e64 v43, v30, v63, s[0:1]
	v_cndmask_b32_e64 v96, v45, v31, s[2:3]
	v_pk_fma_f32 v[58:59], v[86:87], v[58:59], v[94:95]
	v_cndmask_b32_e64 v40, v44, v57, s[0:1]
	v_pk_fma_f32 v[60:61], v[84:85], v[96:97], v[92:93]
	v_pk_fma_f32 v[42:43], v[82:83], v[42:43], v[58:59]
	v_pk_fma_f32 v[40:41], v[80:81], v[40:41], v[60:61]
	v_pk_fma_f32 v[36:37], v[36:37], v[90:91], v[42:43]
	v_cndmask_b32_e64 v42, v53, v51, s[2:3]
	v_cndmask_b32_e64 v43, v56, v54, s[2:3]
	v_pk_fma_f32 v[38:39], v[38:39], v[88:89], v[40:41]
	v_cndmask_b32_e64 v41, v49, v28, s[0:1]
	v_cndmask_b32_e64 v28, v52, v29, s[0:1]
	v_cndmask_b32_e64 v29, v55, v30, s[0:1]
	v_pk_fma_f32 v[42:43], v[86:87], v[42:43], v[94:95]
	v_cndmask_b32_e64 v30, v47, v45, s[2:3]
	v_pk_fma_f32 v[28:29], v[82:83], v[28:29], v[42:43]
	v_cndmask_b32_e64 v31, v50, v48, s[2:3]
	v_pk_fma_f32 v[28:29], v[32:33], v[90:91], v[28:29]
	v_mov_b32_e32 v32, v130
	v_mov_b32_e32 v33, v130
	v_cndmask_b32_e64 v40, v46, v44, s[0:1]
	v_pk_fma_f32 v[30:31], v[84:85], v[30:31], v[92:93]
	v_pk_mul_f32 v[2:3], v[2:3], v[32:33]
	v_mov_b32_e32 v32, v128
	v_mov_b32_e32 v33, v128
	v_pk_fma_f32 v[30:31], v[80:81], v[40:41], v[30:31]
	v_pk_mul_f32 v[6:7], v[6:7], v[32:33]
	v_mov_b32_dpp v40, v20 row_ror:1 row_mask:0xf bank_mask:0xf
	v_mov_b32_dpp v32, v12 row_ror:1 row_mask:0xf bank_mask:0xf
	v_mov_b32_dpp v41, v20 row_ror:2 row_mask:0xf bank_mask:0xf
	v_mov_b32_dpp v33, v12 row_ror:2 row_mask:0xf bank_mask:0xf
	v_pk_fma_f32 v[30:31], v[34:35], v[88:89], v[30:31]
	v_cndmask_b32_e64 v12, v32, v40, s[0:1]
	v_cndmask_b32_e64 v32, v33, v41, s[2:3]
	v_mov_b32_dpp v42, v21 row_ror:1 row_mask:0xf bank_mask:0xf
	v_mov_b32_dpp v33, v13 row_ror:1 row_mask:0xf bank_mask:0xf
	v_mov_b32_dpp v43, v21 row_ror:2 row_mask:0xf bank_mask:0xf
	v_mov_b32_dpp v34, v13 row_ror:2 row_mask:0xf bank_mask:0xf
	v_cndmask_b32_e64 v13, v33, v42, s[0:1]
	v_cndmask_b32_e64 v33, v34, v43, s[2:3]
	v_mov_b32_dpp v44, v22 row_ror:1 row_mask:0xf bank_mask:0xf
	v_mov_b32_dpp v34, v14 row_ror:1 row_mask:0xf bank_mask:0xf
	v_mov_b32_dpp v45, v22 row_ror:2 row_mask:0xf bank_mask:0xf
	v_mov_b32_dpp v35, v14 row_ror:2 row_mask:0xf bank_mask:0xf
	v_cndmask_b32_e64 v14, v34, v44, s[0:1]
	v_cndmask_b32_e64 v34, v35, v45, s[2:3]
	v_mov_b32_dpp v46, v23 row_ror:1 row_mask:0xf bank_mask:0xf
	v_mov_b32_dpp v35, v15 row_ror:1 row_mask:0xf bank_mask:0xf
	v_mov_b32_dpp v47, v23 row_ror:2 row_mask:0xf bank_mask:0xf
	v_mov_b32_dpp v48, v15 row_ror:2 row_mask:0xf bank_mask:0xf
	v_cndmask_b32_e64 v15, v35, v46, s[0:1]
	v_cndmask_b32_e64 v35, v48, v47, s[2:3]
	v_pk_fma_f32 v[34:35], v[74:75], v[34:35], v[78:79]
	v_pk_fma_f32 v[32:33], v[72:73], v[32:33], v[76:77]
	v_pk_fma_f32 v[14:15], v[70:71], v[14:15], v[34:35]
	v_pk_fma_f32 v[12:13], v[68:69], v[12:13], v[32:33]
	v_pk_fma_f32 v[14:15], v[22:23], v[66:67], v[14:15]
	v_mul_f32_e32 v22, 0xbfb8aa3b, v30
	v_mul_f32_e32 v23, 0xbfb8aa3b, v31
	v_exp_f32_e32 v22, v22
	v_exp_f32_e32 v23, v23
	v_pk_fma_f32 v[12:13], v[20:21], v[64:65], v[12:13]
	v_add_f32_e32 v20, 1.0, v22
	v_add_f32_e32 v21, 1.0, v23
	v_mul_f32_e32 v22, 0xbfb8aa3b, v28
	v_mul_f32_e32 v23, 0xbfb8aa3b, v29
	v_exp_f32_e32 v22, v22
	v_exp_f32_e32 v23, v23
	v_rcp_f32_e32 v20, v20
	v_rcp_f32_e32 v21, v21
	v_add_f32_e32 v22, 1.0, v22
	v_add_f32_e32 v23, 1.0, v23
	v_rcp_f32_e32 v22, v22
	v_rcp_f32_e32 v23, v23
	v_pk_mul_f32 v[20:21], v[30:31], v[20:21]
	v_pk_mul_f32 v[12:13], v[20:21], v[12:13]
	v_pk_mul_f32 v[20:21], v[28:29], v[22:23]
	v_pk_mul_f32 v[14:15], v[20:21], v[14:15]
	v_mov_b32_dpp v29, v4 row_ror:2 row_mask:0xf bank_mask:0xf
	v_mov_b32_dpp v31, v5 row_ror:2 row_mask:0xf bank_mask:0xf
	v_mov_b32_dpp v33, v6 row_ror:2 row_mask:0xf bank_mask:0xf
	v_mov_b32_dpp v35, v7 row_ror:2 row_mask:0xf bank_mask:0xf
	v_cvt_pk_bf16_f32 v12, v12, v13
	v_cvt_pk_bf16_f32 v13, v14, v15
	v_mov_b32_dpp v28, v4 row_ror:1 row_mask:0xf bank_mask:0xf
	v_cndmask_b32_e64 v14, v41, v29, s[2:3]
; DI unsigned cvtpk(float lo, float hi) { f32x2_t v = {lo, hi}; bf16x2_t b = __builtin_convertvector(v, bf16x2_t); return __builtin_bit_cast(unsigned, b); }
; DI float silu_f(float x) { return x * frcp(1.f + fexp2(-x * LOG2E)); }
; #define PG8_BAR __builtin_amdgcn_s_barrier()
; template <int CTRL> DI float dpp_ror(float v) { return __builtin_bit_cast(float, __builtin_amdgcn_update_dpp(0, __builtin_bit_cast(int, v), CTRL, 0xf, 0xf, false)); }
; template <class Epi, class Sched>
; DI void gemm_phase(LAS unsigned char* lds, const int K, const Sched& S, const Epi& E, const int wid) {
;     ...
;         if (!has_next) break;
; #pragma unroll
;         for (int a = 0; a < 2; ++a)
; #pragma unroll
;             for (int b = 0; b < 2; ++b)
; #pragma unroll
;                 for (int m = 0; m < 4; ++m)
; #pragma unroll
;                     for (int n = 0; n < 2; ++n) acc[a][b][m][n] = (f32x4){0.f, 0.f, 0.f, 0.f};
;         cur = nxt; cA = nA; cB = nB; ++ui;
;         if (wr == 1) PG8_BAR;
;     template <int GV>
;     DI void conv_cols(const Acc& acc, const Unit& u, int ai, int n, int G, int f, int fr, const float (&rs)[4], bool samp, int sb, const f32x4 (&cw)[4], f32x4 (&cg)[4], bf16_t* actp) const {
;     ...
;         for (int m = 0; m < 4; ++m) {
;             f32x4 p1, p2;
; #pragma unroll
;             for (int j = 0; j < 4; ++j) {
;                 const float prev = (m == 0) ? Hh[j] : X[m - 1][j];
;                 const float a1 = dpp_ror<0x121>(X[m][j]), b1 = dpp_ror<0x121>(prev);
;                 const float a2 = dpp_ror<0x122>(X[m][j]), b2 = dpp_ror<0x122>(prev);
;                 p1[j] = (fr >= 1) ? a1 : b1; p2[j] = (fr >= 2) ? a2 : b2;
;             }
;             const f32x4 c = cw[3] + cw[0] * p2 + cw[1] * p1 + cw[2] * X[m];
;             if (GV == 0) cg[m] = c;
;             else { u32x2 wv; wv.x = cvtpk(silu_f(cg[m][0]) * c[0], silu_f(cg[m][1]) * c[1]); wv.y = cvtpk(silu_f(cg[m][2]) * c[2], silu_f(cg[m][3]) * c[3]);
;                 *(u32x2*)(actp + (size_t)(m * 16) * FFP) = wv; }
	v_mov_b32_dpp v30, v5 row_ror:1 row_mask:0xf bank_mask:0xf
	v_cndmask_b32_e64 v15, v43, v31, s[2:3]
	v_mov_b32_dpp v32, v6 row_ror:1 row_mask:0xf bank_mask:0xf
	v_cndmask_b32_e64 v22, v45, v33, s[2:3]
	v_mov_b32_dpp v34, v7 row_ror:1 row_mask:0xf bank_mask:0xf
	v_cndmask_b32_e64 v23, v47, v35, s[2:3]
	global_store_dwordx2 v[112:113], v[12:13], off offset:8
	v_cndmask_b32_e64 v12, v40, v28, s[0:1]
	v_cndmask_b32_e64 v13, v42, v30, s[0:1]
	v_cndmask_b32_e64 v20, v44, v32, s[0:1]
	v_cndmask_b32_e64 v21, v46, v34, s[0:1]
	v_pk_fma_f32 v[22:23], v[74:75], v[22:23], v[78:79]
	v_pk_fma_f32 v[14:15], v[72:73], v[14:15], v[76:77]
	v_pk_mul_f32 v[0:1], v[0:1], v[130:131]
	v_pk_fma_f32 v[12:13], v[68:69], v[12:13], v[14:15]
	v_pk_fma_f32 v[14:15], v[70:71], v[20:21], v[22:23]
	v_pk_fma_f32 v[4:5], v[4:5], v[64:65], v[12:13]
	v_pk_fma_f32 v[6:7], v[6:7], v[66:67], v[14:15]
	v_mul_f32_e32 v14, 0xbfb8aa3b, v38
	v_mul_f32_e32 v15, 0xbfb8aa3b, v39
	v_exp_f32_e32 v14, v14
	v_exp_f32_e32 v15, v15
	v_add_f32_e32 v12, 1.0, v14
	v_add_f32_e32 v13, 1.0, v15
	v_mul_f32_e32 v14, 0xbfb8aa3b, v36
	v_mul_f32_e32 v15, 0xbfb8aa3b, v37
	v_exp_f32_e32 v14, v14
	v_exp_f32_e32 v15, v15
	v_rcp_f32_e32 v12, v12
	v_rcp_f32_e32 v13, v13
	v_add_f32_e32 v14, 1.0, v14
	v_add_f32_e32 v15, 1.0, v15
	v_rcp_f32_e32 v14, v14
	v_rcp_f32_e32 v15, v15
	v_pk_mul_f32 v[12:13], v[38:39], v[12:13]
	v_pk_mul_f32 v[4:5], v[12:13], v[4:5]
	v_pk_mul_f32 v[12:13], v[36:37], v[14:15]
	v_mov_b32_dpp v21, v0 row_ror:2 row_mask:0xf bank_mask:0xf
	v_pk_mul_f32 v[6:7], v[12:13], v[6:7]
	v_mov_b32_dpp v23, v1 row_ror:2 row_mask:0xf bank_mask:0xf
	v_cvt_pk_bf16_f32 v4, v4, v5
	v_cvt_pk_bf16_f32 v5, v6, v7
	v_mov_b32_dpp v20, v0 row_ror:1 row_mask:0xf bank_mask:0xf
	v_cndmask_b32_e64 v6, v29, v21, s[2:3]
	v_mov_b32_dpp v22, v1 row_ror:1 row_mask:0xf bank_mask:0xf
	v_cndmask_b32_e64 v7, v31, v23, s[2:3]
	global_store_dwordx2 v[114:115], v[4:5], off offset:2056
	v_cndmask_b32_e64 v4, v28, v20, s[0:1]
	v_cndmask_b32_e64 v5, v30, v22, s[0:1]
	v_pk_fma_f32 v[6:7], v[72:73], v[6:7], v[76:77]
	v_pk_fma_f32 v[4:5], v[68:69], v[4:5], v[6:7]
	v_mul_f32_e32 v6, 0xbfb8aa3b, v26
	v_mul_f32_e32 v7, 0xbfb8aa3b, v27
	v_exp_f32_e32 v6, v6
	v_exp_f32_e32 v7, v7
	v_pk_fma_f32 v[0:1], v[0:1], v[64:65], v[4:5]
	v_add_f32_e32 v4, 1.0, v6
	v_add_f32_e32 v5, 1.0, v7
	v_mul_f32_e32 v6, 0xbfb8aa3b, v24
	v_mul_f32_e32 v7, 0xbfb8aa3b, v25
	v_exp_f32_e32 v6, v6
	v_exp_f32_e32 v7, v7
	v_rcp_f32_e32 v4, v4
	v_rcp_f32_e32 v5, v5
	v_add_f32_e32 v6, 1.0, v6
	v_add_f32_e32 v7, 1.0, v7
	v_mov_b32_dpp v29, v2 row_ror:2 row_mask:0xf bank_mask:0xf
	v_mov_b32_dpp v31, v3 row_ror:2 row_mask:0xf bank_mask:0xf
	v_rcp_f32_e32 v6, v6
	v_rcp_f32_e32 v7, v7
	v_mov_b32_dpp v28, v2 row_ror:1 row_mask:0xf bank_mask:0xf
	v_cndmask_b32_e64 v14, v33, v29, s[2:3]
	v_mov_b32_dpp v30, v3 row_ror:1 row_mask:0xf bank_mask:0xf
	v_cndmask_b32_e64 v15, v35, v31, s[2:3]
	v_cndmask_b32_e64 v12, v32, v28, s[0:1]
	v_cndmask_b32_e64 v13, v34, v30, s[0:1]
	v_pk_fma_f32 v[14:15], v[74:75], v[14:15], v[78:79]
	v_pk_mul_f32 v[4:5], v[26:27], v[4:5]
	v_pk_fma_f32 v[12:13], v[70:71], v[12:13], v[14:15]
	v_pk_mul_f32 v[0:1], v[4:5], v[0:1]
	v_pk_fma_f32 v[2:3], v[2:3], v[66:67], v[12:13]
	v_pk_mul_f32 v[4:5], v[24:25], v[6:7]
	v_cvt_pk_bf16_f32 v0, v0, v1
	v_pk_mul_f32 v[2:3], v[4:5], v[2:3]
	v_cvt_pk_bf16_f32 v1, v2, v3
	global_store_dwordx2 v[116:117], v[0:1], off offset:8
	v_mov_b32_dpp v5, v10 row_ror:2 row_mask:0xf bank_mask:0xf
	v_mov_b32_dpp v1, v8 row_ror:2 row_mask:0xf bank_mask:0xf
	v_cndmask_b32_e64 v2, v21, v1, s[2:3]
	v_mov_b32_dpp v3, v9 row_ror:2 row_mask:0xf bank_mask:0xf
	v_cndmask_b32_e64 v6, v29, v5, s[2:3]
	v_mov_b32_dpp v7, v11 row_ror:2 row_mask:0xf bank_mask:0xf
	v_mov_b32_dpp v0, v8 row_ror:1 row_mask:0xf bank_mask:0xf
	v_mov_b32_dpp v1, v9 row_ror:1 row_mask:0xf bank_mask:0xf
	v_cndmask_b32_e64 v3, v23, v3, s[2:3]
	v_mov_b32_dpp v4, v10 row_ror:1 row_mask:0xf bank_mask:0xf
	v_mov_b32_dpp v5, v11 row_ror:1 row_mask:0xf bank_mask:0xf
	v_cndmask_b32_e64 v7, v31, v7, s[2:3]
	v_cndmask_b32_e64 v0, v20, v0, s[0:1]
	v_cndmask_b32_e64 v1, v22, v1, s[0:1]
	v_cndmask_b32_e64 v4, v28, v4, s[0:1]
	v_cndmask_b32_e64 v5, v30, v5, s[0:1]
	v_pk_fma_f32 v[6:7], v[74:75], v[6:7], v[78:79]
	v_pk_fma_f32 v[2:3], v[72:73], v[2:3], v[76:77]
	s_mov_b64 s[4:5], -1
	v_pk_fma_f32 v[0:1], v[68:69], v[0:1], v[2:3]
	v_pk_fma_f32 v[2:3], v[70:71], v[4:5], v[6:7]
	v_mul_f32_e32 v4, 0xbfb8aa3b, v18
	v_mul_f32_e32 v5, 0xbfb8aa3b, v19
	v_exp_f32_e32 v4, v4
	v_exp_f32_e32 v5, v5
	v_mul_f32_e32 v6, 0xbfb8aa3b, v16
	v_mul_f32_e32 v7, 0xbfb8aa3b, v17
	v_exp_f32_e32 v6, v6
	v_exp_f32_e32 v7, v7
	v_add_f32_e32 v4, 1.0, v4
	v_add_f32_e32 v5, 1.0, v5
	v_rcp_f32_e32 v4, v4
	v_rcp_f32_e32 v5, v5
	v_add_f32_e32 v6, 1.0, v6
	v_add_f32_e32 v7, 1.0, v7
	v_rcp_f32_e32 v6, v6
	v_rcp_f32_e32 v7, v7
	v_pk_fma_f32 v[0:1], v[8:9], v[64:65], v[0:1]
	v_pk_mul_f32 v[4:5], v[18:19], v[4:5]
	v_pk_fma_f32 v[2:3], v[10:11], v[66:67], v[2:3]
	v_pk_mul_f32 v[0:1], v[4:5], v[0:1]
	v_pk_mul_f32 v[4:5], v[16:17], v[6:7]
	v_cvt_pk_bf16_f32 v0, v0, v1
	v_pk_mul_f32 v[2:3], v[4:5], v[2:3]
	v_readlane_b32 s75, v249, 34
	v_cvt_pk_bf16_f32 v1, v2, v3
	v_add_co_u32_e32 v2, vcc, 0x85000, v112
	s_nop 1
	v_addc_co_u32_e32 v3, vcc, 0, v113, vcc
	global_store_dwordx2 v[2:3], v[0:1], off offset:2056
	s_andn2_b64 vcc, exec, s[40:41]
	s_cbranch_vccnz .LBB0_809
	v_readlane_b32 s4, v249, 28
	v_readlane_b32 s5, v249, 29
	s_and_b64 vcc, exec, s[4:5]
	s_cbranch_vccnz .LBB0_808
	s_barrier
	s_branch .LBB0_808

; __global__ void __launch_bounds__(512, 2) fwd(Args args) {
	.amdhsa_kernel _Z3fwd4Args
		.amdhsa_group_segment_fixed_size 0
		.amdhsa_private_segment_fixed_size 0
		.amdhsa_kernarg_size 464
		.amdhsa_user_sgpr_count 2
		.amdhsa_user_sgpr_dispatch_ptr 0
		.amdhsa_user_sgpr_queue_ptr 0
		.amdhsa_user_sgpr_kernarg_segment_ptr 1
		.amdhsa_user_sgpr_dispatch_id 0
		.amdhsa_user_sgpr_kernarg_preload_length 0
		.amdhsa_user_sgpr_kernarg_preload_offset 0
		.amdhsa_user_sgpr_private_segment_size 0
		.amdhsa_uses_dynamic_stack 0
		.amdhsa_enable_private_segment 0
		.amdhsa_system_sgpr_workgroup_id_x 1
		.amdhsa_system_sgpr_workgroup_id_y 0
		.amdhsa_system_sgpr_workgroup_id_z 0
		.amdhsa_system_sgpr_workgroup_info 0
		.amdhsa_system_vgpr_workitem_id 2
		.amdhsa_next_free_vgpr 251
		.amdhsa_next_free_sgpr 102
		.amdhsa_accum_offset 252
		.amdhsa_reserve_vcc 1
		.amdhsa_float_round_mode_32 0
		.amdhsa_float_round_mode_16_64 0
		.amdhsa_float_denorm_mode_32 3
		.amdhsa_float_denorm_mode_16_64 3
		.amdhsa_dx10_clamp 1
		.amdhsa_ieee_mode 1
		.amdhsa_fp16_overflow 0
		.amdhsa_tg_split 0
		.amdhsa_exception_fp_ieee_invalid_op 0
		.amdhsa_exception_fp_denorm_src 0
		.amdhsa_exception_fp_ieee_div_zero 0
		.amdhsa_exception_fp_ieee_overflow 0
		.amdhsa_exception_fp_ieee_underflow 0
		.amdhsa_exception_fp_ieee_inexact 0
		.amdhsa_exception_int_div_zero 0
	.end_amdhsa_kernel

; __global__ void __launch_bounds__(512, 2) fwd(Args args) {
amdhsa.kernels:
  - .agpr_count:     0
    .args:
      - .offset:         0
        .size:           208
        .value_kind:     by_value
      - .offset:         208
        .size:           4
        .value_kind:     hidden_block_count_x
      - .offset:         212
        .size:           4
        .value_kind:     hidden_block_count_y
      - .offset:         216
        .size:           4
        .value_kind:     hidden_block_count_z
      - .offset:         220
        .size:           2
        .value_kind:     hidden_group_size_x
      - .offset:         222
        .size:           2
        .value_kind:     hidden_group_size_y
      - .offset:         224
        .size:           2
        .value_kind:     hidden_group_size_z
      - .offset:         226
        .size:           2
        .value_kind:     hidden_remainder_x
      - .offset:         228
        .size:           2
        .value_kind:     hidden_remainder_y
      - .offset:         230
        .size:           2
        .value_kind:     hidden_remainder_z
      - .offset:         248
        .size:           8
        .value_kind:     hidden_global_offset_x
      - .offset:         256
        .size:           8
        .value_kind:     hidden_global_offset_y
      - .offset:         264
        .size:           8
        .value_kind:     hidden_global_offset_z
      - .offset:         272
        .size:           2
        .value_kind:     hidden_grid_dims
      - .offset:         296
        .size:           8
        .value_kind:     hidden_multigrid_sync_arg
      - .offset:         328
        .size:           4
        .value_kind:     hidden_dynamic_lds_size
    .group_segment_fixed_size: 0
    .kernarg_segment_align: 8
    .kernarg_segment_size: 464
    .language:       OpenCL C
    .language_version:
      - 2
      - 0
    .max_flat_workgroup_size: 512
    .name:           _Z3fwd4Args
    .private_segment_fixed_size: 0
    .sgpr_count:     108
    .sgpr_spill_count: 209
    .symbol:         _Z3fwd4Args.kd
    .uniform_work_group_size: 1
    .uses_dynamic_stack: false
    .vgpr_count:     251
    .vgpr_spill_count: 0
    .wavefront_size: 64
